# pool_up / mla_up epilogues: five vmcnt(0) waits placed behind fresh stores relaxed to cover only the older loads (store acks no longer waited for)
# baseline (speedup 1.0000x reference)
; __device__ __forceinline__ float sigmoidf_(float g) { return __builtin_amdgcn_rcpf(1.f + __expf(-g)); }
; __device__ __forceinline__ u32x4 pack8(const f32x4& a, const f32x4& b) { u32x4 w; w.x = cvt_pk_bf16(a[0], a[1]); w.y = cvt_pk_bf16(a[2], a[3]); w.z = cvt_pk_bf16(b[0], b[1]); w.w = cvt_pk_bf16(b[2], b[3]); return w; }
; __device__ __forceinline__ void unpack8(const u32x4& w, float (&v)[8]) { v[0] = bf_lo(w.x); v[1] = bf_hi(w.x); v[2] = bf_lo(w.y); v[3] = bf_hi(w.y); v[4] = bf_lo(w.z); v[5] = bf_hi(w.z); v[6] = bf_lo(w.w); v[7] = bf_hi(w.w); }
;     __device__ __forceinline__ void apply(const Ld& d, int row, int c0, int, int, int, const f32x4& a0, const f32x4& b0, const f32x4& a1, const f32x4& b1) const { half(d.g0, row, c0, a0, b0); half(d.g1, row, c0 + 128, a1, b1); }
;     __device__ __forceinline__ void operator()(const f32x4 (&acc)[2][2][4][2], const Unit& u, int wr, int wc, int fr, int fq) const {
;         const int c0 = u.pn * BM + wc * 32 + 8 * fq;
; #pragma unroll
;         for (int ai = 0; ai < 2; ++ai)
; #pragma unroll
;             for (int mp = 0; mp < 4; mp += 2) {
;                 typename F::Ld ld[2];
; #pragma unroll
;                 for (int m = 0; m < 2; ++m) f.load(ld[m], u.pm * BM + ai * HALF + wr * 64 + (mp + m) * 16 + fr, c0, u.pn, fq);
; #pragma unroll
;                 for (int m = 0; m < 2; ++m) f.apply(ld[m], u.pm * BM + ai * HALF + wr * 64 + (mp + m) * 16 + fr, c0, u.pn, wc, fq, acc[ai][0][mp + m][0], acc[ai][0][mp + m][1], acc[ai][1][mp + m][0], acc[ai][1][mp + m][1]);
;             }
;     }
;     __device__ __forceinline__ void half(const u32x4& gw, const u32x4& pw, int row, int col, const f32x4& a, const f32x4& b) const {
;         float g[8]; unpack8(gw, g); float p[8]; unpack8(pw, p);
;         f32x4 r0, r1;
; #pragma unroll
;         for (int i = 0; i < 4; ++i) { r0[i] = a[i] * sigmoidf_(g[i]) + p[i]; r1[i] = b[i] * sigmoidf_(g[4 + i]) + p[4 + i]; }
;         *(u32x4*)(merged + (size_t)row * 1024 + col) = pack8(r0, r1);
;     }
;     __device__ __forceinline__ void apply(const Ld& d, int row, int c0, int, int, int, const f32x4& a0, const f32x4& b0, const f32x4& a1, const f32x4& b1) const { half(d.g0, d.p0, row, c0, a0, b0); half(d.g1, d.p1, row, c0 + 128, a1, b1); }
.LBB0_283:
	s_and_b64 vcc, exec, s[0:1]
	s_cbranch_vccz .LBB0_285
	v_lshl_or_b32 v134, s71, 8, v241
	v_ashrrev_i32_e32 v135, 31, v134
	v_readlane_b32 s0, v254, 62
	v_lshlrev_b64 v[164:165], 1, v[134:135]
	v_readlane_b32 s1, v254, 63
	v_mov_b64_e32 v[168:169], s[74:75]
	s_nop 0
	v_lshl_add_u64 v[162:163], s[0:1], 0, v[164:165]
	s_lshl_b32 s0, s63, 8
	v_add_u32_e32 v166, s0, v17
	v_mad_i64_i32 v[134:135], s[22:23], v166, s29, v[168:169]
	v_lshl_add_u64 v[134:135], v[134:135], 0, v[164:165]
	v_add_co_u32_e32 v136, vcc, 0x1000, v134
	v_or_b32_e32 v0, 16, v166
	s_nop 0
	v_addc_co_u32_e32 v137, vcc, 0, v135, vcc
	global_load_dwordx4 v[158:161], v[136:137], off offset:3072
	global_load_dwordx4 v[150:153], v[136:137], off offset:3328
	global_load_dwordx4 v[170:173], v[134:135], off offset:2048
	global_load_dwordx4 v[154:157], v[134:135], off offset:2304
	v_mad_i64_i32 v[134:135], s[22:23], v0, s29, v[168:169]
	v_lshl_add_u64 v[134:135], v[134:135], 0, v[164:165]
	v_add_co_u32_e32 v136, vcc, 0x1000, v134
	v_ashrrev_i32_e32 v167, 31, v166
	s_nop 0
	v_addc_co_u32_e32 v137, vcc, 0, v135, vcc
	global_load_dwordx4 v[146:149], v[136:137], off offset:3072
	global_load_dwordx4 v[138:141], v[136:137], off offset:3328
	global_load_dwordx4 v[142:145], v[134:135], off offset:2048
	s_nop 0
	global_load_dwordx4 v[134:137], v[134:135], off offset:2304
	s_waitcnt vmcnt(0)
	v_lshlrev_b32_e32 v0, 16, v158
	v_mul_f32_e32 v0, 0xbfb8aa3b, v0
	v_exp_f32_e32 v0, v0
	v_lshlrev_b32_e32 v175, 16, v160
	v_lshlrev_b32_e32 v177, 16, v170
	v_and_b32_e32 v158, 0xffff0000, v158
	v_add_f32_e32 v0, 1.0, v0
	v_rcp_f32_e32 v0, v0
	v_lshlrev_b32_e32 v179, 16, v172
	v_and_b32_e32 v160, 0xffff0000, v160
	v_and_b32_e32 v170, 0xffff0000, v170
	v_fmac_f32_e32 v177, v130, v0
	v_mul_f32_e32 v0, 0xbfb8aa3b, v175
	v_exp_f32_e32 v0, v0
	v_lshlrev_b32_e32 v174, 16, v159
	v_and_b32_e32 v172, 0xffff0000, v172
	v_lshlrev_b32_e32 v176, 16, v161
	v_add_f32_e32 v0, 1.0, v0
	v_rcp_f32_e32 v0, v0
	v_lshlrev_b32_e32 v178, 16, v171
	v_and_b32_e32 v159, 0xffff0000, v159
	v_lshlrev_b32_e32 v180, 16, v173
	v_fmac_f32_e32 v179, v126, v0
	v_mul_f32_e32 v0, 0xbfb8aa3b, v158
	v_exp_f32_e32 v0, v0
	v_and_b32_e32 v161, 0xffff0000, v161
	v_and_b32_e32 v171, 0xffff0000, v171
	v_and_b32_e32 v173, 0xffff0000, v173
	v_add_f32_e32 v0, 1.0, v0
	v_rcp_f32_e32 v0, v0
	s_nop 0
	v_fmac_f32_e32 v170, v131, v0
	v_mul_f32_e32 v0, 0xbfb8aa3b, v160
	v_exp_f32_e32 v0, v0
	v_cvt_pk_bf16_f32 v158, v177, v170
	s_nop 0
	v_add_f32_e32 v0, 1.0, v0
	v_rcp_f32_e32 v0, v0
	s_nop 0
	v_fmac_f32_e32 v172, v127, v0
	v_mul_f32_e32 v0, 0xbfb8aa3b, v174
	v_exp_f32_e32 v0, v0
	v_add_u32_e32 v174, s0, v236
	v_add_f32_e32 v0, 1.0, v0
	v_rcp_f32_e32 v0, v0
	s_nop 0
	v_fmac_f32_e32 v178, v132, v0
	v_mul_f32_e32 v0, 0xbfb8aa3b, v176
	v_exp_f32_e32 v0, v0
	s_nop 0
	v_add_f32_e32 v0, 1.0, v0
	v_rcp_f32_e32 v0, v0
	s_nop 0
	v_fmac_f32_e32 v180, v128, v0
	v_mul_f32_e32 v0, 0xbfb8aa3b, v159
	v_exp_f32_e32 v0, v0
	s_nop 0
	v_add_f32_e32 v0, 1.0, v0
	v_rcp_f32_e32 v0, v0
	s_nop 0
	v_fmac_f32_e32 v171, v133, v0
	v_mul_f32_e32 v0, 0xbfb8aa3b, v161
	v_exp_f32_e32 v0, v0
	v_cvt_pk_bf16_f32 v159, v178, v171
	v_lshlrev_b64 v[170:171], 11, v[166:167]
	v_cvt_pk_bf16_f32 v160, v179, v172
	v_add_f32_e32 v0, 1.0, v0
	v_rcp_f32_e32 v0, v0
	v_lshl_add_u64 v[170:171], v[162:163], 0, v[170:171]
	v_lshlrev_b32_e32 v172, 16, v156
	v_and_b32_e32 v156, 0xffff0000, v156
	v_fmac_f32_e32 v173, v129, v0
	v_lshlrev_b32_e32 v0, 16, v150
	v_mul_f32_e32 v0, 0xbfb8aa3b, v0
	v_exp_f32_e32 v0, v0
	v_cvt_pk_bf16_f32 v161, v180, v173
	global_store_dwordx4 v[170:171], v[158:161], off
	v_and_b32_e32 v150, 0xffff0000, v150
	v_add_f32_e32 v0, 1.0, v0
	v_rcp_f32_e32 v0, v0
	v_lshlrev_b32_e32 v159, 16, v152
	v_lshlrev_b32_e32 v161, 16, v154
	v_and_b32_e32 v152, 0xffff0000, v152
	v_fmac_f32_e32 v161, v122, v0
	v_mul_f32_e32 v0, 0xbfb8aa3b, v159
	v_exp_f32_e32 v0, v0
	v_and_b32_e32 v154, 0xffff0000, v154
	v_lshlrev_b32_e32 v158, 16, v151
	v_lshlrev_b32_e32 v160, 16, v153
	v_add_f32_e32 v0, 1.0, v0
	v_rcp_f32_e32 v0, v0
	v_lshlrev_b32_e32 v167, 16, v155
	v_and_b32_e32 v151, 0xffff0000, v151
	v_lshlrev_b32_e32 v173, 16, v157
	v_fmac_f32_e32 v172, v118, v0
	v_mul_f32_e32 v0, 0xbfb8aa3b, v150
	v_exp_f32_e32 v0, v0
	v_and_b32_e32 v153, 0xffff0000, v153
	v_and_b32_e32 v155, 0xffff0000, v155
	v_and_b32_e32 v157, 0xffff0000, v157
	v_add_f32_e32 v0, 1.0, v0
	v_rcp_f32_e32 v0, v0
	s_nop 0
	v_fmac_f32_e32 v154, v123, v0
	v_mul_f32_e32 v0, 0xbfb8aa3b, v152
	v_exp_f32_e32 v0, v0
	v_cvt_pk_bf16_f32 v150, v161, v154
	v_lshlrev_b32_e32 v154, 16, v142
	v_and_b32_e32 v142, 0xffff0000, v142
	v_add_f32_e32 v0, 1.0, v0
	v_rcp_f32_e32 v0, v0
	s_nop 0
	v_fmac_f32_e32 v156, v119, v0
	v_mul_f32_e32 v0, 0xbfb8aa3b, v158
	v_exp_f32_e32 v0, v0
	s_nop 0
	v_add_f32_e32 v0, 1.0, v0
	v_rcp_f32_e32 v0, v0
	s_nop 0
	v_fmac_f32_e32 v167, v124, v0
	v_mul_f32_e32 v0, 0xbfb8aa3b, v160
	v_exp_f32_e32 v0, v0
	s_nop 0
	v_add_f32_e32 v0, 1.0, v0
	v_rcp_f32_e32 v0, v0
	s_nop 0
	v_fmac_f32_e32 v173, v120, v0
	v_mul_f32_e32 v0, 0xbfb8aa3b, v151
	v_exp_f32_e32 v0, v0
	s_nop 0
	v_add_f32_e32 v0, 1.0, v0
	v_rcp_f32_e32 v0, v0
	s_nop 0
	v_fmac_f32_e32 v155, v125, v0
	v_mul_f32_e32 v0, 0xbfb8aa3b, v153
	v_exp_f32_e32 v0, v0
	v_cvt_pk_bf16_f32 v151, v167, v155
	v_cvt_pk_bf16_f32 v152, v172, v156
	v_lshlrev_b32_e32 v156, 16, v144
	v_add_f32_e32 v0, 1.0, v0
	v_rcp_f32_e32 v0, v0
	v_and_b32_e32 v144, 0xffff0000, v144
	v_lshlrev_b32_e32 v155, 16, v143
	v_and_b32_e32 v143, 0xffff0000, v143
	v_fmac_f32_e32 v157, v121, v0
	v_lshlrev_b32_e32 v0, 16, v146
	v_mul_f32_e32 v0, 0xbfb8aa3b, v0
	v_exp_f32_e32 v0, v0
	v_cvt_pk_bf16_f32 v153, v173, v157
; __device__ __forceinline__ float sigmoidf_(float g) { return __builtin_amdgcn_rcpf(1.f + __expf(-g)); }
; __device__ __forceinline__ u32x4 pack8(const f32x4& a, const f32x4& b) { u32x4 w; w.x = cvt_pk_bf16(a[0], a[1]); w.y = cvt_pk_bf16(a[2], a[3]); w.z = cvt_pk_bf16(b[0], b[1]); w.w = cvt_pk_bf16(b[2], b[3]); return w; }
; __device__ __forceinline__ void unpack8(const u32x4& w, float (&v)[8]) { v[0] = bf_lo(w.x); v[1] = bf_hi(w.x); v[2] = bf_lo(w.y); v[3] = bf_hi(w.y); v[4] = bf_lo(w.z); v[5] = bf_hi(w.z); v[6] = bf_lo(w.w); v[7] = bf_hi(w.w); }
;     __device__ __forceinline__ void apply(const Ld& d, int row, int c0, int, int, int, const f32x4& a0, const f32x4& b0, const f32x4& a1, const f32x4& b1) const { half(d.g0, row, c0, a0, b0); half(d.g1, row, c0 + 128, a1, b1); }
;     __device__ __forceinline__ void operator()(const f32x4 (&acc)[2][2][4][2], const Unit& u, int wr, int wc, int fr, int fq) const {
;         const int c0 = u.pn * BM + wc * 32 + 8 * fq;
; #pragma unroll
;         for (int ai = 0; ai < 2; ++ai)
; #pragma unroll
;             for (int mp = 0; mp < 4; mp += 2) {
;                 typename F::Ld ld[2];
; #pragma unroll
;                 for (int m = 0; m < 2; ++m) f.load(ld[m], u.pm * BM + ai * HALF + wr * 64 + (mp + m) * 16 + fr, c0, u.pn, fq);
; #pragma unroll
;                 for (int m = 0; m < 2; ++m) f.apply(ld[m], u.pm * BM + ai * HALF + wr * 64 + (mp + m) * 16 + fr, c0, u.pn, wc, fq, acc[ai][0][mp + m][0], acc[ai][0][mp + m][1], acc[ai][1][mp + m][0], acc[ai][1][mp + m][1]);
;             }
;     }
;     __device__ __forceinline__ void half(const u32x4& gw, const u32x4& pw, int row, int col, const f32x4& a, const f32x4& b) const {
;         float g[8]; unpack8(gw, g); float p[8]; unpack8(pw, p);
;         f32x4 r0, r1;
; #pragma unroll
;         for (int i = 0; i < 4; ++i) { r0[i] = a[i] * sigmoidf_(g[i]) + p[i]; r1[i] = b[i] * sigmoidf_(g[4 + i]) + p[4 + i]; }
;         *(u32x4*)(merged + (size_t)row * 1024 + col) = pack8(r0, r1);
;     }
;     __device__ __forceinline__ void apply(const Ld& d, int row, int c0, int, int, int, const f32x4& a0, const f32x4& b0, const f32x4& a1, const f32x4& b1) const { half(d.g0, d.p0, row, c0, a0, b0); half(d.g1, d.p1, row, c0 + 128, a1, b1); }
	global_store_dwordx4 v[170:171], v[150:153], off offset:256
	v_and_b32_e32 v146, 0xffff0000, v146
	v_add_f32_e32 v0, 1.0, v0
	v_rcp_f32_e32 v0, v0
	v_lshlrev_b32_e32 v152, 16, v148
	v_and_b32_e32 v148, 0xffff0000, v148
	v_lshlrev_b32_e32 v151, 16, v147
	v_fmac_f32_e32 v154, v114, v0
	v_mul_f32_e32 v0, 0xbfb8aa3b, v152
	v_exp_f32_e32 v0, v0
	v_lshlrev_b32_e32 v153, 16, v149
	v_and_b32_e32 v147, 0xffff0000, v147
	v_lshlrev_b32_e32 v157, 16, v145
	v_add_f32_e32 v0, 1.0, v0
	v_rcp_f32_e32 v0, v0
	v_and_b32_e32 v149, 0xffff0000, v149
	v_and_b32_e32 v145, 0xffff0000, v145
	v_add_u32_e32 v150, s0, v235
	v_fmac_f32_e32 v156, v110, v0
	v_mul_f32_e32 v0, 0xbfb8aa3b, v146
	v_exp_f32_e32 v0, v0
	s_nop 0
	v_add_f32_e32 v0, 1.0, v0
	v_rcp_f32_e32 v0, v0
	s_nop 0
	v_fmac_f32_e32 v142, v115, v0
	v_mul_f32_e32 v0, 0xbfb8aa3b, v148
	v_exp_f32_e32 v0, v0
	v_cvt_pk_bf16_f32 v142, v154, v142
	v_lshlrev_b32_e32 v148, 16, v135
	v_and_b32_e32 v135, 0xffff0000, v135
	v_add_f32_e32 v0, 1.0, v0
	v_rcp_f32_e32 v0, v0
	s_nop 0
	v_fmac_f32_e32 v144, v111, v0
	v_mul_f32_e32 v0, 0xbfb8aa3b, v151
	v_exp_f32_e32 v0, v0
	v_ashrrev_i32_e32 v151, 31, v150
	v_add_f32_e32 v0, 1.0, v0
	v_rcp_f32_e32 v0, v0
	s_nop 0
	v_fmac_f32_e32 v155, v116, v0
	v_mul_f32_e32 v0, 0xbfb8aa3b, v153
	v_exp_f32_e32 v0, v0
	s_nop 0
	v_add_f32_e32 v0, 1.0, v0
	v_rcp_f32_e32 v0, v0
	s_nop 0
	v_fmac_f32_e32 v157, v112, v0
	v_mul_f32_e32 v0, 0xbfb8aa3b, v147
	v_exp_f32_e32 v0, v0
	v_lshlrev_b64 v[146:147], 11, v[150:151]
	v_lshl_add_u64 v[146:147], v[162:163], 0, v[146:147]
	v_lshlrev_b32_e32 v150, 16, v137
	v_add_f32_e32 v0, 1.0, v0
	v_rcp_f32_e32 v0, v0
	v_and_b32_e32 v137, 0xffff0000, v137
	v_fmac_f32_e32 v143, v117, v0
	v_mul_f32_e32 v0, 0xbfb8aa3b, v149
	v_exp_f32_e32 v0, v0
	v_cvt_pk_bf16_f32 v143, v155, v143
	v_cvt_pk_bf16_f32 v144, v156, v144
	v_lshlrev_b32_e32 v149, 16, v136
	v_add_f32_e32 v0, 1.0, v0
	v_rcp_f32_e32 v0, v0
	v_and_b32_e32 v136, 0xffff0000, v136
	v_fmac_f32_e32 v145, v113, v0
	v_lshlrev_b32_e32 v0, 16, v138
	v_mul_f32_e32 v0, 0xbfb8aa3b, v0
	v_exp_f32_e32 v0, v0
	v_cvt_pk_bf16_f32 v145, v157, v145
	global_store_dwordx4 v[146:147], v[142:145], off
	v_and_b32_e32 v138, 0xffff0000, v138
	v_add_f32_e32 v0, 1.0, v0
	v_rcp_f32_e32 v0, v0
	v_lshlrev_b32_e32 v143, 16, v140
	v_lshlrev_b32_e32 v145, 16, v134
	v_and_b32_e32 v140, 0xffff0000, v140
	v_fmac_f32_e32 v145, v106, v0
	v_mul_f32_e32 v0, 0xbfb8aa3b, v143
	v_exp_f32_e32 v0, v0
	v_and_b32_e32 v134, 0xffff0000, v134
	v_lshlrev_b32_e32 v142, 16, v139
	v_lshlrev_b32_e32 v144, 16, v141
	v_add_f32_e32 v0, 1.0, v0
	v_rcp_f32_e32 v0, v0
	v_and_b32_e32 v139, 0xffff0000, v139
	v_and_b32_e32 v141, 0xffff0000, v141
	v_fmac_f32_e32 v149, v102, v0
	v_mul_f32_e32 v0, 0xbfb8aa3b, v138
	v_exp_f32_e32 v0, v0
	s_nop 0
	v_add_f32_e32 v0, 1.0, v0
	v_rcp_f32_e32 v0, v0
	s_nop 0
	v_fmac_f32_e32 v134, v107, v0
	v_mul_f32_e32 v0, 0xbfb8aa3b, v140
	v_exp_f32_e32 v0, v0
	v_cvt_pk_bf16_f32 v134, v145, v134
	s_nop 0
	v_add_f32_e32 v0, 1.0, v0
	v_rcp_f32_e32 v0, v0
	s_nop 0
	v_fmac_f32_e32 v136, v103, v0
	v_mul_f32_e32 v0, 0xbfb8aa3b, v142
	v_exp_f32_e32 v0, v0
	s_nop 0
	v_add_f32_e32 v0, 1.0, v0
	v_rcp_f32_e32 v0, v0
	s_nop 0
	v_fmac_f32_e32 v148, v108, v0
	v_mul_f32_e32 v0, 0xbfb8aa3b, v144
	v_exp_f32_e32 v0, v0
	s_nop 0
	v_add_f32_e32 v0, 1.0, v0
	v_rcp_f32_e32 v0, v0
	s_nop 0
	v_fmac_f32_e32 v150, v104, v0
	v_mul_f32_e32 v0, 0xbfb8aa3b, v139
	v_exp_f32_e32 v0, v0
	s_nop 0
	v_add_f32_e32 v0, 1.0, v0
	v_rcp_f32_e32 v0, v0
	s_nop 0
	v_fmac_f32_e32 v135, v109, v0
	v_mul_f32_e32 v0, 0xbfb8aa3b, v141
	v_exp_f32_e32 v0, v0
	v_cvt_pk_bf16_f32 v135, v148, v135
	v_cvt_pk_bf16_f32 v136, v149, v136
	s_nop 0
	v_add_f32_e32 v0, 1.0, v0
	v_rcp_f32_e32 v0, v0
	s_nop 0
	v_fmac_f32_e32 v137, v105, v0
	v_or_b32_e32 v0, 32, v166
	v_cvt_pk_bf16_f32 v137, v150, v137
	global_store_dwordx4 v[146:147], v[134:137], off offset:256
	s_nop 1
	v_mad_i64_i32 v[134:135], s[22:23], v0, s29, v[168:169]
	v_lshl_add_u64 v[134:135], v[134:135], 0, v[164:165]
	v_add_co_u32_e32 v136, vcc, s98, v134
	v_or_b32_e32 v0, 48, v166
	s_nop 0
	v_addc_co_u32_e32 v137, vcc, 0, v135, vcc
	global_load_dwordx4 v[154:157], v[136:137], off offset:3072
	global_load_dwordx4 v[150:153], v[136:137], off offset:3328
	global_load_dwordx4 v[158:161], v[134:135], off offset:2048
	global_load_dwordx4 v[170:173], v[134:135], off offset:2304
	v_mad_i64_i32 v[134:135], s[22:23], v0, s29, v[168:169]
	v_lshl_add_u64 v[134:135], v[134:135], 0, v[164:165]
	v_add_co_u32_e32 v136, vcc, s98, v134
	s_waitcnt vmcnt(0)
; __device__ __forceinline__ float sigmoidf_(float g) { return __builtin_amdgcn_rcpf(1.f + __expf(-g)); }
; __device__ __forceinline__ u32x4 pack8(const f32x4& a, const f32x4& b) { u32x4 w; w.x = cvt_pk_bf16(a[0], a[1]); w.y = cvt_pk_bf16(a[2], a[3]); w.z = cvt_pk_bf16(b[0], b[1]); w.w = cvt_pk_bf16(b[2], b[3]); return w; }
; __device__ __forceinline__ void unpack8(const u32x4& w, float (&v)[8]) { v[0] = bf_lo(w.x); v[1] = bf_hi(w.x); v[2] = bf_lo(w.y); v[3] = bf_hi(w.y); v[4] = bf_lo(w.z); v[5] = bf_hi(w.z); v[6] = bf_lo(w.w); v[7] = bf_hi(w.w); }
;     __device__ __forceinline__ void apply(const Ld& d, int row, int c0, int, int, int, const f32x4& a0, const f32x4& b0, const f32x4& a1, const f32x4& b1) const { half(d.g0, row, c0, a0, b0); half(d.g1, row, c0 + 128, a1, b1); }
;     __device__ __forceinline__ void operator()(const f32x4 (&acc)[2][2][4][2], const Unit& u, int wr, int wc, int fr, int fq) const {
;         const int c0 = u.pn * BM + wc * 32 + 8 * fq;
; #pragma unroll
;         for (int ai = 0; ai < 2; ++ai)
; #pragma unroll
;             for (int mp = 0; mp < 4; mp += 2) {
;                 typename F::Ld ld[2];
; #pragma unroll
;                 for (int m = 0; m < 2; ++m) f.load(ld[m], u.pm * BM + ai * HALF + wr * 64 + (mp + m) * 16 + fr, c0, u.pn, fq);
; #pragma unroll
;                 for (int m = 0; m < 2; ++m) f.apply(ld[m], u.pm * BM + ai * HALF + wr * 64 + (mp + m) * 16 + fr, c0, u.pn, wc, fq, acc[ai][0][mp + m][0], acc[ai][0][mp + m][1], acc[ai][1][mp + m][0], acc[ai][1][mp + m][1]);
;             }
;     }
;     __device__ __forceinline__ void half(const u32x4& gw, const u32x4& pw, int row, int col, const f32x4& a, const f32x4& b) const {
;         float g[8]; unpack8(gw, g); float p[8]; unpack8(pw, p);
;         f32x4 r0, r1;
; #pragma unroll
;         for (int i = 0; i < 4; ++i) { r0[i] = a[i] * sigmoidf_(g[i]) + p[i]; r1[i] = b[i] * sigmoidf_(g[4 + i]) + p[4 + i]; }
;         *(u32x4*)(merged + (size_t)row * 1024 + col) = pack8(r0, r1);
;     }
;     __device__ __forceinline__ void apply(const Ld& d, int row, int c0, int, int, int, const f32x4& a0, const f32x4& b0, const f32x4& a1, const f32x4& b1) const { half(d.g0, d.p0, row, c0, a0, b0); half(d.g1, d.p1, row, c0 + 128, a1, b1); }
	v_lshlrev_b32_e32 v0, 16, v154
	v_mul_f32_e32 v0, 0xbfb8aa3b, v0
	v_exp_f32_e32 v0, v0
	v_lshlrev_b32_e32 v175, 16, v156
	v_lshlrev_b32_e32 v177, 16, v158
	v_and_b32_e32 v154, 0xffff0000, v154
	v_add_f32_e32 v0, 1.0, v0
	v_rcp_f32_e32 v0, v0
	v_lshlrev_b32_e32 v179, 16, v160
	v_and_b32_e32 v156, 0xffff0000, v156
	v_and_b32_e32 v158, 0xffff0000, v158
	v_fmac_f32_e32 v177, v98, v0
	v_mul_f32_e32 v0, 0xbfb8aa3b, v175
	v_exp_f32_e32 v0, v0
	v_lshlrev_b32_e32 v167, 16, v155
	v_and_b32_e32 v160, 0xffff0000, v160
	v_lshlrev_b32_e32 v176, 16, v157
	v_add_f32_e32 v0, 1.0, v0
	v_rcp_f32_e32 v0, v0
	v_lshlrev_b32_e32 v178, 16, v159
	v_and_b32_e32 v155, 0xffff0000, v155
	v_lshlrev_b32_e32 v180, 16, v161
	v_fmac_f32_e32 v179, v94, v0
	v_mul_f32_e32 v0, 0xbfb8aa3b, v154
	v_exp_f32_e32 v0, v0
	v_and_b32_e32 v157, 0xffff0000, v157
	v_and_b32_e32 v159, 0xffff0000, v159
	v_and_b32_e32 v161, 0xffff0000, v161
	v_add_f32_e32 v0, 1.0, v0
	v_rcp_f32_e32 v0, v0
	v_addc_co_u32_e32 v137, vcc, 0, v135, vcc
	global_load_dwordx4 v[146:149], v[136:137], off offset:3072
	global_load_dwordx4 v[138:141], v[136:137], off offset:3328
	global_load_dwordx4 v[142:145], v[134:135], off offset:2048
	s_nop 0
	global_load_dwordx4 v[134:137], v[134:135], off offset:2304
	v_fmac_f32_e32 v158, v99, v0
	v_mul_f32_e32 v0, 0xbfb8aa3b, v156
	v_exp_f32_e32 v0, v0
	v_ashrrev_i32_e32 v175, 31, v174
	v_cvt_pk_bf16_f32 v154, v177, v158
	v_add_f32_e32 v0, 1.0, v0
	v_rcp_f32_e32 v0, v0
	s_nop 0
	v_fmac_f32_e32 v160, v95, v0
	v_mul_f32_e32 v0, 0xbfb8aa3b, v167
	v_exp_f32_e32 v0, v0
	v_and_b32_e32 v167, 0xffff0000, v171
	v_add_f32_e32 v0, 1.0, v0
	v_rcp_f32_e32 v0, v0
	s_nop 0
	v_fmac_f32_e32 v178, v100, v0
	v_mul_f32_e32 v0, 0xbfb8aa3b, v176
	v_exp_f32_e32 v0, v0
	s_nop 0
	v_add_f32_e32 v0, 1.0, v0
	v_rcp_f32_e32 v0, v0
	s_nop 0
	v_fmac_f32_e32 v180, v96, v0
	v_mul_f32_e32 v0, 0xbfb8aa3b, v155
	v_exp_f32_e32 v0, v0
	s_nop 0
	v_add_f32_e32 v0, 1.0, v0
	v_rcp_f32_e32 v0, v0
	s_nop 0
	v_fmac_f32_e32 v159, v101, v0
	v_mul_f32_e32 v0, 0xbfb8aa3b, v157
	v_exp_f32_e32 v0, v0
	v_cvt_pk_bf16_f32 v155, v178, v159
	v_lshlrev_b64 v[158:159], 11, v[174:175]
	v_cvt_pk_bf16_f32 v156, v179, v160
	v_add_f32_e32 v0, 1.0, v0
	v_rcp_f32_e32 v0, v0
	v_lshl_add_u64 v[158:159], v[162:163], 0, v[158:159]
	v_and_b32_e32 v160, 0xffff0000, v170
	v_fmac_f32_e32 v161, v97, v0
	v_lshlrev_b32_e32 v0, 16, v150
	v_mul_f32_e32 v0, 0xbfb8aa3b, v0
	v_exp_f32_e32 v0, v0
	v_cvt_pk_bf16_f32 v157, v180, v161
	global_store_dwordx4 v[158:159], v[154:157], off
	v_and_b32_e32 v150, 0xffff0000, v150
	v_add_f32_e32 v0, 1.0, v0
	v_rcp_f32_e32 v0, v0
	v_lshlrev_b32_e32 v155, 16, v152
	v_lshlrev_b32_e32 v157, 16, v170
	v_lshlrev_b32_e32 v170, 16, v172
	v_fmac_f32_e32 v157, v90, v0
	v_mul_f32_e32 v0, 0xbfb8aa3b, v155
	v_exp_f32_e32 v0, v0
	v_and_b32_e32 v152, 0xffff0000, v152
	v_lshlrev_b32_e32 v154, 16, v151
	v_lshlrev_b32_e32 v161, 16, v171
	v_add_f32_e32 v0, 1.0, v0
	v_rcp_f32_e32 v0, v0
	v_and_b32_e32 v171, 0xffff0000, v172
	v_lshlrev_b32_e32 v156, 16, v153
	v_and_b32_e32 v151, 0xffff0000, v151
	v_fmac_f32_e32 v170, v86, v0
	v_mul_f32_e32 v0, 0xbfb8aa3b, v150
	v_exp_f32_e32 v0, v0
	v_lshlrev_b32_e32 v172, 16, v173
	v_and_b32_e32 v153, 0xffff0000, v153
	v_and_b32_e32 v173, 0xffff0000, v173
	v_add_f32_e32 v0, 1.0, v0
	v_rcp_f32_e32 v0, v0
	s_waitcnt vmcnt(1)
	v_lshlrev_b32_e32 v155, 16, v143
	v_and_b32_e32 v143, 0xffff0000, v143
	v_fmac_f32_e32 v160, v91, v0
	v_mul_f32_e32 v0, 0xbfb8aa3b, v152
	v_exp_f32_e32 v0, v0
	v_cvt_pk_bf16_f32 v150, v157, v160
	v_lshlrev_b32_e32 v157, 16, v145
	v_and_b32_e32 v145, 0xffff0000, v145
	v_add_f32_e32 v0, 1.0, v0
	v_rcp_f32_e32 v0, v0
	s_nop 0
	v_fmac_f32_e32 v171, v87, v0
	v_mul_f32_e32 v0, 0xbfb8aa3b, v154
	v_exp_f32_e32 v0, v0
	v_lshlrev_b32_e32 v154, 16, v142
	v_and_b32_e32 v142, 0xffff0000, v142
	v_add_f32_e32 v0, 1.0, v0
	v_rcp_f32_e32 v0, v0
	s_nop 0
	v_fmac_f32_e32 v161, v92, v0
	v_mul_f32_e32 v0, 0xbfb8aa3b, v156
	v_exp_f32_e32 v0, v0
	v_lshlrev_b32_e32 v156, 16, v144
	v_and_b32_e32 v144, 0xffff0000, v144
	v_add_f32_e32 v0, 1.0, v0
	v_rcp_f32_e32 v0, v0
	s_nop 0
	v_fmac_f32_e32 v172, v88, v0
	v_mul_f32_e32 v0, 0xbfb8aa3b, v151
	v_exp_f32_e32 v0, v0
	s_nop 0
	v_add_f32_e32 v0, 1.0, v0
	v_rcp_f32_e32 v0, v0
	s_nop 0
	v_fmac_f32_e32 v167, v93, v0
	v_mul_f32_e32 v0, 0xbfb8aa3b, v153
	v_exp_f32_e32 v0, v0
	v_cvt_pk_bf16_f32 v151, v161, v167
	v_cvt_pk_bf16_f32 v152, v170, v171
	s_nop 0
	v_add_f32_e32 v0, 1.0, v0
	v_rcp_f32_e32 v0, v0
	s_nop 0
	v_fmac_f32_e32 v173, v89, v0
	v_lshlrev_b32_e32 v0, 16, v146
	v_mul_f32_e32 v0, 0xbfb8aa3b, v0
	v_exp_f32_e32 v0, v0
	v_cvt_pk_bf16_f32 v153, v172, v173
	global_store_dwordx4 v[158:159], v[150:153], off offset:256
	v_and_b32_e32 v146, 0xffff0000, v146
	v_add_f32_e32 v0, 1.0, v0
	v_rcp_f32_e32 v0, v0
	v_lshlrev_b32_e32 v152, 16, v148
	v_and_b32_e32 v148, 0xffff0000, v148
	v_lshlrev_b32_e32 v151, 16, v147
	v_fmac_f32_e32 v154, v82, v0
	v_mul_f32_e32 v0, 0xbfb8aa3b, v152
	v_exp_f32_e32 v0, v0
	v_lshlrev_b32_e32 v153, 16, v149
	v_and_b32_e32 v147, 0xffff0000, v147
	v_and_b32_e32 v149, 0xffff0000, v149
	v_add_f32_e32 v0, 1.0, v0
	v_rcp_f32_e32 v0, v0
	v_add_u32_e32 v150, s0, v237
	v_fmac_f32_e32 v156, v78, v0
	v_mul_f32_e32 v0, 0xbfb8aa3b, v146
	v_exp_f32_e32 v0, v0
	s_nop 0
	v_add_f32_e32 v0, 1.0, v0
	v_rcp_f32_e32 v0, v0
	s_nop 0
	v_fmac_f32_e32 v142, v83, v0
	v_mul_f32_e32 v0, 0xbfb8aa3b, v148
	v_exp_f32_e32 v0, v0
	v_cvt_pk_bf16_f32 v142, v154, v142
	v_lshlrev_b32_e32 v148, 16, v135
	v_and_b32_e32 v135, 0xffff0000, v135
	v_add_f32_e32 v0, 1.0, v0
	v_rcp_f32_e32 v0, v0
	v_add_u32_e32 v154, 0x80, v166
	v_fmac_f32_e32 v144, v79, v0
	v_mul_f32_e32 v0, 0xbfb8aa3b, v151
; __device__ __forceinline__ float sigmoidf_(float g) { return __builtin_amdgcn_rcpf(1.f + __expf(-g)); }
; __device__ __forceinline__ u32x4 pack8(const f32x4& a, const f32x4& b) { u32x4 w; w.x = cvt_pk_bf16(a[0], a[1]); w.y = cvt_pk_bf16(a[2], a[3]); w.z = cvt_pk_bf16(b[0], b[1]); w.w = cvt_pk_bf16(b[2], b[3]); return w; }
; __device__ __forceinline__ void unpack8(const u32x4& w, float (&v)[8]) { v[0] = bf_lo(w.x); v[1] = bf_hi(w.x); v[2] = bf_lo(w.y); v[3] = bf_hi(w.y); v[4] = bf_lo(w.z); v[5] = bf_hi(w.z); v[6] = bf_lo(w.w); v[7] = bf_hi(w.w); }
;     __device__ __forceinline__ void apply(const Ld& d, int row, int c0, int, int, int, const f32x4& a0, const f32x4& b0, const f32x4& a1, const f32x4& b1) const { half(d.g0, row, c0, a0, b0); half(d.g1, row, c0 + 128, a1, b1); }
;     __device__ __forceinline__ void operator()(const f32x4 (&acc)[2][2][4][2], const Unit& u, int wr, int wc, int fr, int fq) const {
;         const int c0 = u.pn * BM + wc * 32 + 8 * fq;
; #pragma unroll
;         for (int ai = 0; ai < 2; ++ai)
; #pragma unroll
;             for (int mp = 0; mp < 4; mp += 2) {
;                 typename F::Ld ld[2];
; #pragma unroll
;                 for (int m = 0; m < 2; ++m) f.load(ld[m], u.pm * BM + ai * HALF + wr * 64 + (mp + m) * 16 + fr, c0, u.pn, fq);
; #pragma unroll
;                 for (int m = 0; m < 2; ++m) f.apply(ld[m], u.pm * BM + ai * HALF + wr * 64 + (mp + m) * 16 + fr, c0, u.pn, wc, fq, acc[ai][0][mp + m][0], acc[ai][0][mp + m][1], acc[ai][1][mp + m][0], acc[ai][1][mp + m][1]);
;             }
;     }
;     __device__ __forceinline__ void half(const u32x4& gw, const u32x4& pw, int row, int col, const f32x4& a, const f32x4& b) const {
;         float g[8]; unpack8(gw, g); float p[8]; unpack8(pw, p);
;         f32x4 r0, r1;
; #pragma unroll
;         for (int i = 0; i < 4; ++i) { r0[i] = a[i] * sigmoidf_(g[i]) + p[i]; r1[i] = b[i] * sigmoidf_(g[4 + i]) + p[4 + i]; }
;         *(u32x4*)(merged + (size_t)row * 1024 + col) = pack8(r0, r1);
;     }
;     __device__ __forceinline__ void apply(const Ld& d, int row, int c0, int, int, int, const f32x4& a0, const f32x4& b0, const f32x4& a1, const f32x4& b1) const { half(d.g0, d.p0, row, c0, a0, b0); half(d.g1, d.p1, row, c0 + 128, a1, b1); }
	v_exp_f32_e32 v0, v0
	v_ashrrev_i32_e32 v151, 31, v150
	v_add_f32_e32 v0, 1.0, v0
	v_rcp_f32_e32 v0, v0
	s_nop 0
	v_fmac_f32_e32 v155, v84, v0
	v_mul_f32_e32 v0, 0xbfb8aa3b, v153
	v_exp_f32_e32 v0, v0
	s_nop 0
	v_add_f32_e32 v0, 1.0, v0
	v_rcp_f32_e32 v0, v0
	s_nop 0
	v_fmac_f32_e32 v157, v80, v0
	v_mul_f32_e32 v0, 0xbfb8aa3b, v147
	v_exp_f32_e32 v0, v0
	v_lshlrev_b64 v[146:147], 11, v[150:151]
	v_lshl_add_u64 v[146:147], v[162:163], 0, v[146:147]
	v_lshlrev_b32_e32 v150, 16, v137
	v_add_f32_e32 v0, 1.0, v0
	v_rcp_f32_e32 v0, v0
	v_and_b32_e32 v137, 0xffff0000, v137
	v_fmac_f32_e32 v143, v85, v0
	v_mul_f32_e32 v0, 0xbfb8aa3b, v149
	v_exp_f32_e32 v0, v0
	v_cvt_pk_bf16_f32 v143, v155, v143
	v_cvt_pk_bf16_f32 v144, v156, v144
	v_lshlrev_b32_e32 v149, 16, v136
	v_add_f32_e32 v0, 1.0, v0
	v_rcp_f32_e32 v0, v0
	v_and_b32_e32 v136, 0xffff0000, v136
	v_ashrrev_i32_e32 v155, 31, v154
	v_fmac_f32_e32 v145, v81, v0
	v_lshlrev_b32_e32 v0, 16, v138
	v_mul_f32_e32 v0, 0xbfb8aa3b, v0
	v_exp_f32_e32 v0, v0
	v_cvt_pk_bf16_f32 v145, v157, v145
	global_store_dwordx4 v[146:147], v[142:145], off
	v_and_b32_e32 v138, 0xffff0000, v138
	v_add_f32_e32 v0, 1.0, v0
	v_rcp_f32_e32 v0, v0
	v_lshlrev_b32_e32 v143, 16, v140
	v_lshlrev_b32_e32 v145, 16, v134
	v_and_b32_e32 v140, 0xffff0000, v140
	v_fmac_f32_e32 v145, v74, v0
	v_mul_f32_e32 v0, 0xbfb8aa3b, v143
	v_exp_f32_e32 v0, v0
	v_and_b32_e32 v134, 0xffff0000, v134
	v_lshlrev_b32_e32 v142, 16, v139
	v_lshlrev_b32_e32 v144, 16, v141
	v_add_f32_e32 v0, 1.0, v0
	v_rcp_f32_e32 v0, v0
	v_and_b32_e32 v139, 0xffff0000, v139
	v_and_b32_e32 v141, 0xffff0000, v141
	v_fmac_f32_e32 v149, v70, v0
	v_mul_f32_e32 v0, 0xbfb8aa3b, v138
	v_exp_f32_e32 v0, v0
	s_nop 0
	v_add_f32_e32 v0, 1.0, v0
	v_rcp_f32_e32 v0, v0
	s_nop 0
	v_fmac_f32_e32 v134, v75, v0
	v_mul_f32_e32 v0, 0xbfb8aa3b, v140
	v_exp_f32_e32 v0, v0
	v_cvt_pk_bf16_f32 v134, v145, v134
	s_nop 0
	v_add_f32_e32 v0, 1.0, v0
	v_rcp_f32_e32 v0, v0
	s_nop 0
	v_fmac_f32_e32 v136, v71, v0
	v_mul_f32_e32 v0, 0xbfb8aa3b, v142
	v_exp_f32_e32 v0, v0
	s_nop 0
	v_add_f32_e32 v0, 1.0, v0
	v_rcp_f32_e32 v0, v0
	s_nop 0
	v_fmac_f32_e32 v148, v76, v0
	v_mul_f32_e32 v0, 0xbfb8aa3b, v144
	v_exp_f32_e32 v0, v0
	s_nop 0
	v_add_f32_e32 v0, 1.0, v0
	v_rcp_f32_e32 v0, v0
	s_nop 0
	v_fmac_f32_e32 v150, v72, v0
	v_mul_f32_e32 v0, 0xbfb8aa3b, v139
	v_exp_f32_e32 v0, v0
	s_nop 0
	v_add_f32_e32 v0, 1.0, v0
	v_rcp_f32_e32 v0, v0
	s_nop 0
	v_fmac_f32_e32 v135, v77, v0
	v_mul_f32_e32 v0, 0xbfb8aa3b, v141
	v_exp_f32_e32 v0, v0
	v_cvt_pk_bf16_f32 v135, v148, v135
	v_cvt_pk_bf16_f32 v136, v149, v136
	s_nop 0
	v_add_f32_e32 v0, 1.0, v0
	v_rcp_f32_e32 v0, v0
	s_nop 0
	v_fmac_f32_e32 v137, v73, v0
	v_cvt_pk_bf16_f32 v137, v150, v137
	global_store_dwordx4 v[146:147], v[134:137], off offset:256
	v_add_u32_e32 v0, 0x90, v166
	s_nop 0
	v_mad_i64_i32 v[134:135], s[22:23], v154, s29, v[168:169]
	v_lshl_add_u64 v[134:135], v[134:135], 0, v[164:165]
	v_add_co_u32_e32 v136, vcc, s98, v134
	v_lshlrev_b64 v[154:155], 11, v[154:155]
	s_nop 0
	v_addc_co_u32_e32 v137, vcc, 0, v135, vcc
	global_load_dwordx4 v[156:159], v[136:137], off offset:3072
	global_load_dwordx4 v[150:153], v[136:137], off offset:3328
	global_load_dwordx4 v[170:173], v[134:135], off offset:2048
	global_load_dwordx4 v[174:177], v[134:135], off offset:2304
	v_mad_i64_i32 v[134:135], s[22:23], v0, s29, v[168:169]
	v_lshl_add_u64 v[134:135], v[134:135], 0, v[164:165]
	v_add_co_u32_e32 v136, vcc, s98, v134
	v_lshl_add_u64 v[154:155], v[162:163], 0, v[154:155]
	s_nop 0
	v_addc_co_u32_e32 v137, vcc, 0, v135, vcc
	global_load_dwordx4 v[146:149], v[136:137], off offset:3072
	global_load_dwordx4 v[138:141], v[136:137], off offset:3328
	global_load_dwordx4 v[142:145], v[134:135], off offset:2048
	s_nop 0
	global_load_dwordx4 v[134:137], v[134:135], off offset:2304
	s_waitcnt vmcnt(0)
	v_lshlrev_b32_e32 v0, 16, v156
	v_mul_f32_e32 v0, 0xbfb8aa3b, v0
	v_exp_f32_e32 v0, v0
	v_lshlrev_b32_e32 v161, 16, v158
	v_lshlrev_b32_e32 v178, 16, v170
	v_and_b32_e32 v156, 0xffff0000, v156
	v_add_f32_e32 v0, 1.0, v0
	v_rcp_f32_e32 v0, v0
	v_lshlrev_b32_e32 v180, 16, v172
	v_and_b32_e32 v158, 0xffff0000, v158
	v_and_b32_e32 v170, 0xffff0000, v170
	v_fmac_f32_e32 v178, v66, v0
	v_mul_f32_e32 v0, 0xbfb8aa3b, v161
	v_exp_f32_e32 v0, v0
	v_lshlrev_b32_e32 v160, 16, v157
	v_and_b32_e32 v172, 0xffff0000, v172
	v_lshlrev_b32_e32 v167, 16, v159
	v_add_f32_e32 v0, 1.0, v0
	v_rcp_f32_e32 v0, v0
	v_lshlrev_b32_e32 v179, 16, v171
	v_and_b32_e32 v157, 0xffff0000, v157
	v_lshlrev_b32_e32 v181, 16, v173
	v_fmac_f32_e32 v180, v62, v0
	v_mul_f32_e32 v0, 0xbfb8aa3b, v156
	v_exp_f32_e32 v0, v0
	v_and_b32_e32 v159, 0xffff0000, v159
	v_and_b32_e32 v171, 0xffff0000, v171
	v_and_b32_e32 v173, 0xffff0000, v173
	v_add_f32_e32 v0, 1.0, v0
	v_rcp_f32_e32 v0, v0
	v_lshlrev_b32_e32 v161, 16, v175
	v_fmac_f32_e32 v170, v67, v0
	v_mul_f32_e32 v0, 0xbfb8aa3b, v158
	v_exp_f32_e32 v0, v0
	v_cvt_pk_bf16_f32 v156, v178, v170
	v_lshlrev_b32_e32 v170, 16, v176
	v_add_f32_e32 v0, 1.0, v0
	v_rcp_f32_e32 v0, v0
	s_nop 0
	v_fmac_f32_e32 v172, v63, v0
	v_mul_f32_e32 v0, 0xbfb8aa3b, v160
	v_exp_f32_e32 v0, v0
	v_and_b32_e32 v160, 0xffff0000, v174
	v_add_f32_e32 v0, 1.0, v0
	v_rcp_f32_e32 v0, v0
	s_nop 0
	v_fmac_f32_e32 v179, v68, v0
	v_mul_f32_e32 v0, 0xbfb8aa3b, v167
	v_exp_f32_e32 v0, v0
	v_and_b32_e32 v167, 0xffff0000, v175
	v_add_f32_e32 v0, 1.0, v0
	v_rcp_f32_e32 v0, v0
	s_nop 0
	v_fmac_f32_e32 v181, v64, v0
	v_mul_f32_e32 v0, 0xbfb8aa3b, v157
	v_exp_f32_e32 v0, v0
	s_nop 0
	v_add_f32_e32 v0, 1.0, v0
	v_rcp_f32_e32 v0, v0
	s_nop 0
	v_fmac_f32_e32 v171, v69, v0
	v_mul_f32_e32 v0, 0xbfb8aa3b, v159
	v_exp_f32_e32 v0, v0
; __device__ __forceinline__ float sigmoidf_(float g) { return __builtin_amdgcn_rcpf(1.f + __expf(-g)); }
; __device__ __forceinline__ u32x4 pack8(const f32x4& a, const f32x4& b) { u32x4 w; w.x = cvt_pk_bf16(a[0], a[1]); w.y = cvt_pk_bf16(a[2], a[3]); w.z = cvt_pk_bf16(b[0], b[1]); w.w = cvt_pk_bf16(b[2], b[3]); return w; }
; __device__ __forceinline__ void unpack8(const u32x4& w, float (&v)[8]) { v[0] = bf_lo(w.x); v[1] = bf_hi(w.x); v[2] = bf_lo(w.y); v[3] = bf_hi(w.y); v[4] = bf_lo(w.z); v[5] = bf_hi(w.z); v[6] = bf_lo(w.w); v[7] = bf_hi(w.w); }
;     __device__ __forceinline__ void apply(const Ld& d, int row, int c0, int, int, int, const f32x4& a0, const f32x4& b0, const f32x4& a1, const f32x4& b1) const { half(d.g0, row, c0, a0, b0); half(d.g1, row, c0 + 128, a1, b1); }
;     __device__ __forceinline__ void operator()(const f32x4 (&acc)[2][2][4][2], const Unit& u, int wr, int wc, int fr, int fq) const {
;         const int c0 = u.pn * BM + wc * 32 + 8 * fq;
; #pragma unroll
;         for (int ai = 0; ai < 2; ++ai)
; #pragma unroll
;             for (int mp = 0; mp < 4; mp += 2) {
;                 typename F::Ld ld[2];
; #pragma unroll
;                 for (int m = 0; m < 2; ++m) f.load(ld[m], u.pm * BM + ai * HALF + wr * 64 + (mp + m) * 16 + fr, c0, u.pn, fq);
; #pragma unroll
;                 for (int m = 0; m < 2; ++m) f.apply(ld[m], u.pm * BM + ai * HALF + wr * 64 + (mp + m) * 16 + fr, c0, u.pn, wc, fq, acc[ai][0][mp + m][0], acc[ai][0][mp + m][1], acc[ai][1][mp + m][0], acc[ai][1][mp + m][1]);
;             }
;     }
;     __device__ __forceinline__ void half(const u32x4& gw, const u32x4& pw, int row, int col, const f32x4& a, const f32x4& b) const {
;         float g[8]; unpack8(gw, g); float p[8]; unpack8(pw, p);
;         f32x4 r0, r1;
; #pragma unroll
;         for (int i = 0; i < 4; ++i) { r0[i] = a[i] * sigmoidf_(g[i]) + p[i]; r1[i] = b[i] * sigmoidf_(g[4 + i]) + p[4 + i]; }
;         *(u32x4*)(merged + (size_t)row * 1024 + col) = pack8(r0, r1);
;     }
;     __device__ __forceinline__ void apply(const Ld& d, int row, int c0, int, int, int, const f32x4& a0, const f32x4& b0, const f32x4& a1, const f32x4& b1) const { half(d.g0, d.p0, row, c0, a0, b0); half(d.g1, d.p1, row, c0 + 128, a1, b1); }
	v_cvt_pk_bf16_f32 v157, v179, v171
	v_cvt_pk_bf16_f32 v158, v180, v172
	v_and_b32_e32 v171, 0xffff0000, v176
	v_add_f32_e32 v0, 1.0, v0
	v_rcp_f32_e32 v0, v0
	v_lshlrev_b32_e32 v172, 16, v177
	v_fmac_f32_e32 v173, v65, v0
	v_lshlrev_b32_e32 v0, 16, v150
	v_mul_f32_e32 v0, 0xbfb8aa3b, v0
	v_exp_f32_e32 v0, v0
	v_cvt_pk_bf16_f32 v159, v181, v173
	global_store_dwordx4 v[154:155], v[156:159], off
	v_and_b32_e32 v150, 0xffff0000, v150
	v_add_f32_e32 v0, 1.0, v0
	v_rcp_f32_e32 v0, v0
	v_lshlrev_b32_e32 v157, 16, v152
	v_lshlrev_b32_e32 v159, 16, v174
	v_and_b32_e32 v152, 0xffff0000, v152
	v_fmac_f32_e32 v159, v58, v0
	v_mul_f32_e32 v0, 0xbfb8aa3b, v157
	v_exp_f32_e32 v0, v0
	v_lshlrev_b32_e32 v156, 16, v151
	v_lshlrev_b32_e32 v158, 16, v153
	v_and_b32_e32 v151, 0xffff0000, v151
	v_add_f32_e32 v0, 1.0, v0
	v_rcp_f32_e32 v0, v0
	v_and_b32_e32 v153, 0xffff0000, v153
	v_and_b32_e32 v173, 0xffff0000, v177
	v_lshlrev_b32_e32 v157, 16, v145
	v_fmac_f32_e32 v170, v54, v0
	v_mul_f32_e32 v0, 0xbfb8aa3b, v150
	v_exp_f32_e32 v0, v0
	v_and_b32_e32 v145, 0xffff0000, v145
	v_add_f32_e32 v0, 1.0, v0
	v_rcp_f32_e32 v0, v0
	s_nop 0
	v_fmac_f32_e32 v160, v59, v0
	v_mul_f32_e32 v0, 0xbfb8aa3b, v152
	v_exp_f32_e32 v0, v0
	v_cvt_pk_bf16_f32 v150, v159, v160
	s_nop 0
	v_add_f32_e32 v0, 1.0, v0
	v_rcp_f32_e32 v0, v0
	s_nop 0
	v_fmac_f32_e32 v171, v55, v0
	v_mul_f32_e32 v0, 0xbfb8aa3b, v156
	v_exp_f32_e32 v0, v0
	v_lshlrev_b32_e32 v156, 16, v144
	v_and_b32_e32 v144, 0xffff0000, v144
	v_add_f32_e32 v0, 1.0, v0
	v_rcp_f32_e32 v0, v0
	s_nop 0
	v_fmac_f32_e32 v161, v60, v0
	v_mul_f32_e32 v0, 0xbfb8aa3b, v158
	v_exp_f32_e32 v0, v0
	s_nop 0
	v_add_f32_e32 v0, 1.0, v0
	v_rcp_f32_e32 v0, v0
	s_nop 0
	v_fmac_f32_e32 v172, v56, v0
	v_mul_f32_e32 v0, 0xbfb8aa3b, v151
	v_exp_f32_e32 v0, v0
	s_nop 0
	v_add_f32_e32 v0, 1.0, v0
	v_rcp_f32_e32 v0, v0
	s_nop 0
	v_fmac_f32_e32 v167, v61, v0
	v_mul_f32_e32 v0, 0xbfb8aa3b, v153
	v_exp_f32_e32 v0, v0
	v_cvt_pk_bf16_f32 v151, v161, v167
	v_cvt_pk_bf16_f32 v152, v170, v171
	s_nop 0
	v_add_f32_e32 v0, 1.0, v0
	v_rcp_f32_e32 v0, v0
	s_nop 0
	v_fmac_f32_e32 v173, v57, v0
	v_lshlrev_b32_e32 v0, 16, v146
	v_mul_f32_e32 v0, 0xbfb8aa3b, v0
	v_exp_f32_e32 v0, v0
	v_cvt_pk_bf16_f32 v153, v172, v173
	global_store_dwordx4 v[154:155], v[150:153], off offset:256
	v_lshlrev_b32_e32 v154, 16, v142
	v_add_f32_e32 v0, 1.0, v0
	v_rcp_f32_e32 v0, v0
	v_lshlrev_b32_e32 v152, 16, v148
	v_and_b32_e32 v146, 0xffff0000, v146
	v_and_b32_e32 v148, 0xffff0000, v148
	v_fmac_f32_e32 v154, v50, v0
	v_mul_f32_e32 v0, 0xbfb8aa3b, v152
	v_exp_f32_e32 v0, v0
	v_and_b32_e32 v142, 0xffff0000, v142
	v_lshlrev_b32_e32 v151, 16, v147
	v_lshlrev_b32_e32 v153, 16, v149
	v_add_f32_e32 v0, 1.0, v0
	v_rcp_f32_e32 v0, v0
	v_lshlrev_b32_e32 v155, 16, v143
	v_and_b32_e32 v147, 0xffff0000, v147
	v_and_b32_e32 v149, 0xffff0000, v149
	v_fmac_f32_e32 v156, v46, v0
	v_mul_f32_e32 v0, 0xbfb8aa3b, v146
	v_exp_f32_e32 v0, v0
	v_and_b32_e32 v143, 0xffff0000, v143
	v_add_u32_e32 v150, s0, v238
	v_add_f32_e32 v0, 1.0, v0
	v_rcp_f32_e32 v0, v0
	s_nop 0
	v_fmac_f32_e32 v142, v51, v0
	v_mul_f32_e32 v0, 0xbfb8aa3b, v148
	v_exp_f32_e32 v0, v0
	v_cvt_pk_bf16_f32 v142, v154, v142
	v_lshlrev_b32_e32 v148, 16, v135
	v_and_b32_e32 v135, 0xffff0000, v135
	v_add_f32_e32 v0, 1.0, v0
	v_rcp_f32_e32 v0, v0
	s_nop 0
	v_fmac_f32_e32 v144, v47, v0
	v_mul_f32_e32 v0, 0xbfb8aa3b, v151
	v_exp_f32_e32 v0, v0
	v_ashrrev_i32_e32 v151, 31, v150
	v_add_f32_e32 v0, 1.0, v0
	v_rcp_f32_e32 v0, v0
	s_nop 0
	v_fmac_f32_e32 v155, v52, v0
	v_mul_f32_e32 v0, 0xbfb8aa3b, v153
	v_exp_f32_e32 v0, v0
	s_nop 0
	v_add_f32_e32 v0, 1.0, v0
	v_rcp_f32_e32 v0, v0
	s_nop 0
	v_fmac_f32_e32 v157, v48, v0
	v_mul_f32_e32 v0, 0xbfb8aa3b, v147
	v_exp_f32_e32 v0, v0
	v_lshlrev_b64 v[146:147], 11, v[150:151]
	v_lshl_add_u64 v[146:147], v[162:163], 0, v[146:147]
	v_lshlrev_b32_e32 v150, 16, v137
	v_add_f32_e32 v0, 1.0, v0
	v_rcp_f32_e32 v0, v0
	v_and_b32_e32 v137, 0xffff0000, v137
	v_fmac_f32_e32 v143, v53, v0
	v_mul_f32_e32 v0, 0xbfb8aa3b, v149
	v_exp_f32_e32 v0, v0
	v_cvt_pk_bf16_f32 v143, v155, v143
	v_cvt_pk_bf16_f32 v144, v156, v144
	v_lshlrev_b32_e32 v149, 16, v136
	v_add_f32_e32 v0, 1.0, v0
	v_rcp_f32_e32 v0, v0
	v_and_b32_e32 v136, 0xffff0000, v136
	v_fmac_f32_e32 v145, v49, v0
	v_lshlrev_b32_e32 v0, 16, v138
	v_mul_f32_e32 v0, 0xbfb8aa3b, v0
	v_exp_f32_e32 v0, v0
	v_cvt_pk_bf16_f32 v145, v157, v145
	global_store_dwordx4 v[146:147], v[142:145], off
	v_and_b32_e32 v138, 0xffff0000, v138
	v_add_f32_e32 v0, 1.0, v0
	v_rcp_f32_e32 v0, v0
	v_lshlrev_b32_e32 v143, 16, v140
	v_lshlrev_b32_e32 v145, 16, v134
	v_and_b32_e32 v140, 0xffff0000, v140
	v_fmac_f32_e32 v145, v42, v0
	v_mul_f32_e32 v0, 0xbfb8aa3b, v143
	v_exp_f32_e32 v0, v0
	v_and_b32_e32 v134, 0xffff0000, v134
	v_lshlrev_b32_e32 v142, 16, v139
	v_lshlrev_b32_e32 v144, 16, v141
	v_add_f32_e32 v0, 1.0, v0
	v_rcp_f32_e32 v0, v0
	v_and_b32_e32 v139, 0xffff0000, v139
	v_and_b32_e32 v141, 0xffff0000, v141
	v_fmac_f32_e32 v149, v38, v0
	v_mul_f32_e32 v0, 0xbfb8aa3b, v138
	v_exp_f32_e32 v0, v0
	s_nop 0
	v_add_f32_e32 v0, 1.0, v0
	v_rcp_f32_e32 v0, v0
	s_nop 0
	v_fmac_f32_e32 v134, v43, v0
	v_mul_f32_e32 v0, 0xbfb8aa3b, v140
	v_exp_f32_e32 v0, v0
	v_cvt_pk_bf16_f32 v134, v145, v134
	s_nop 0
	v_add_f32_e32 v0, 1.0, v0
	v_rcp_f32_e32 v0, v0
	s_nop 0
	v_fmac_f32_e32 v136, v39, v0
	v_mul_f32_e32 v0, 0xbfb8aa3b, v142
	v_exp_f32_e32 v0, v0
	s_nop 0
	v_add_f32_e32 v0, 1.0, v0
	v_rcp_f32_e32 v0, v0
	s_nop 0
	v_fmac_f32_e32 v148, v44, v0
	v_mul_f32_e32 v0, 0xbfb8aa3b, v144
	v_exp_f32_e32 v0, v0
	s_nop 0
	v_add_f32_e32 v0, 1.0, v0
	v_rcp_f32_e32 v0, v0
	s_nop 0
	v_fmac_f32_e32 v150, v40, v0
; __device__ __forceinline__ float sigmoidf_(float g) { return __builtin_amdgcn_rcpf(1.f + __expf(-g)); }
; __device__ __forceinline__ u32x4 pack8(const f32x4& a, const f32x4& b) { u32x4 w; w.x = cvt_pk_bf16(a[0], a[1]); w.y = cvt_pk_bf16(a[2], a[3]); w.z = cvt_pk_bf16(b[0], b[1]); w.w = cvt_pk_bf16(b[2], b[3]); return w; }
; __device__ __forceinline__ void unpack8(const u32x4& w, float (&v)[8]) { v[0] = bf_lo(w.x); v[1] = bf_hi(w.x); v[2] = bf_lo(w.y); v[3] = bf_hi(w.y); v[4] = bf_lo(w.z); v[5] = bf_hi(w.z); v[6] = bf_lo(w.w); v[7] = bf_hi(w.w); }
;     __device__ __forceinline__ void apply(const Ld& d, int row, int c0, int, int, int, const f32x4& a0, const f32x4& b0, const f32x4& a1, const f32x4& b1) const { half(d.g0, row, c0, a0, b0); half(d.g1, row, c0 + 128, a1, b1); }
;     __device__ __forceinline__ void operator()(const f32x4 (&acc)[2][2][4][2], const Unit& u, int wr, int wc, int fr, int fq) const {
;         const int c0 = u.pn * BM + wc * 32 + 8 * fq;
; #pragma unroll
;         for (int ai = 0; ai < 2; ++ai)
; #pragma unroll
;             for (int mp = 0; mp < 4; mp += 2) {
;                 typename F::Ld ld[2];
; #pragma unroll
;                 for (int m = 0; m < 2; ++m) f.load(ld[m], u.pm * BM + ai * HALF + wr * 64 + (mp + m) * 16 + fr, c0, u.pn, fq);
; #pragma unroll
;                 for (int m = 0; m < 2; ++m) f.apply(ld[m], u.pm * BM + ai * HALF + wr * 64 + (mp + m) * 16 + fr, c0, u.pn, wc, fq, acc[ai][0][mp + m][0], acc[ai][0][mp + m][1], acc[ai][1][mp + m][0], acc[ai][1][mp + m][1]);
;             }
;     }
;     __device__ __forceinline__ void half(const u32x4& gw, const u32x4& pw, int row, int col, const f32x4& a, const f32x4& b) const {
;         float g[8]; unpack8(gw, g); float p[8]; unpack8(pw, p);
;         f32x4 r0, r1;
; #pragma unroll
;         for (int i = 0; i < 4; ++i) { r0[i] = a[i] * sigmoidf_(g[i]) + p[i]; r1[i] = b[i] * sigmoidf_(g[4 + i]) + p[4 + i]; }
;         *(u32x4*)(merged + (size_t)row * 1024 + col) = pack8(r0, r1);
;     }
;     __device__ __forceinline__ void apply(const Ld& d, int row, int c0, int, int, int, const f32x4& a0, const f32x4& b0, const f32x4& a1, const f32x4& b1) const { half(d.g0, d.p0, row, c0, a0, b0); half(d.g1, d.p1, row, c0 + 128, a1, b1); }
	v_mul_f32_e32 v0, 0xbfb8aa3b, v139
	v_exp_f32_e32 v0, v0
	s_nop 0
	v_add_f32_e32 v0, 1.0, v0
	v_rcp_f32_e32 v0, v0
	s_nop 0
	v_fmac_f32_e32 v135, v45, v0
	v_mul_f32_e32 v0, 0xbfb8aa3b, v141
	v_exp_f32_e32 v0, v0
	v_cvt_pk_bf16_f32 v135, v148, v135
	v_cvt_pk_bf16_f32 v136, v149, v136
	s_nop 0
	v_add_f32_e32 v0, 1.0, v0
	v_rcp_f32_e32 v0, v0
	s_nop 0
	v_fmac_f32_e32 v137, v41, v0
	v_add_u32_e32 v0, 0xa0, v166
	v_cvt_pk_bf16_f32 v137, v150, v137
	global_store_dwordx4 v[146:147], v[134:137], off offset:256
	s_nop 1
	v_mad_i64_i32 v[134:135], s[22:23], v0, s29, v[168:169]
	v_lshl_add_u64 v[134:135], v[134:135], 0, v[164:165]
	v_add_co_u32_e32 v136, vcc, s98, v134
	v_add_u32_e32 v0, 0xb0, v166
	s_nop 0
	v_addc_co_u32_e32 v137, vcc, 0, v135, vcc
	global_load_dwordx4 v[154:157], v[136:137], off offset:3072
	global_load_dwordx4 v[150:153], v[136:137], off offset:3328
	global_load_dwordx4 v[158:161], v[134:135], off offset:2048
	global_load_dwordx4 v[170:173], v[134:135], off offset:2304
	v_mad_i64_i32 v[134:135], s[22:23], v0, s29, v[168:169]
	v_lshl_add_u64 v[134:135], v[134:135], 0, v[164:165]
	v_add_co_u32_e32 v136, vcc, s98, v134
	v_add_u32_e32 v164, s0, v239
	s_nop 0
	v_addc_co_u32_e32 v137, vcc, 0, v135, vcc
	global_load_dwordx4 v[146:149], v[136:137], off offset:3072
	global_load_dwordx4 v[138:141], v[136:137], off offset:3328
	global_load_dwordx4 v[142:145], v[134:135], off offset:2048
	s_nop 0
	global_load_dwordx4 v[134:137], v[134:135], off offset:2304
	s_waitcnt vmcnt(0)
	v_lshlrev_b32_e32 v0, 16, v154
	v_mul_f32_e32 v0, 0xbfb8aa3b, v0
	v_exp_f32_e32 v0, v0
	v_lshlrev_b32_e32 v166, 16, v156
	v_lshlrev_b32_e32 v168, 16, v158
	v_and_b32_e32 v154, 0xffff0000, v154
	v_add_f32_e32 v0, 1.0, v0
	v_rcp_f32_e32 v0, v0
	v_lshlrev_b32_e32 v174, 16, v160
	v_and_b32_e32 v156, 0xffff0000, v156
	v_and_b32_e32 v158, 0xffff0000, v158
	v_fmac_f32_e32 v168, v34, v0
	v_mul_f32_e32 v0, 0xbfb8aa3b, v166
	v_exp_f32_e32 v0, v0
	v_lshlrev_b32_e32 v165, 16, v155
	v_and_b32_e32 v160, 0xffff0000, v160
	v_lshlrev_b32_e32 v167, 16, v157
	v_add_f32_e32 v0, 1.0, v0
	v_rcp_f32_e32 v0, v0
	v_lshlrev_b32_e32 v169, 16, v159
	v_and_b32_e32 v155, 0xffff0000, v155
	v_lshlrev_b32_e32 v175, 16, v161
	v_fmac_f32_e32 v174, v30, v0
	v_mul_f32_e32 v0, 0xbfb8aa3b, v154
	v_exp_f32_e32 v0, v0
	v_and_b32_e32 v157, 0xffff0000, v157
	v_and_b32_e32 v159, 0xffff0000, v159
	v_and_b32_e32 v161, 0xffff0000, v161
	v_add_f32_e32 v0, 1.0, v0
	v_rcp_f32_e32 v0, v0
	v_and_b32_e32 v166, 0xffff0000, v172
	v_fmac_f32_e32 v158, v35, v0
	v_mul_f32_e32 v0, 0xbfb8aa3b, v156
	v_exp_f32_e32 v0, v0
	v_cvt_pk_bf16_f32 v154, v168, v158
	v_and_b32_e32 v168, 0xffff0000, v173
	v_add_f32_e32 v0, 1.0, v0
	v_rcp_f32_e32 v0, v0
	s_nop 0
	v_fmac_f32_e32 v160, v31, v0
	v_mul_f32_e32 v0, 0xbfb8aa3b, v165
	v_exp_f32_e32 v0, v0
	v_ashrrev_i32_e32 v165, 31, v164
	v_add_f32_e32 v0, 1.0, v0
	v_rcp_f32_e32 v0, v0
	s_nop 0
	v_fmac_f32_e32 v169, v36, v0
	v_mul_f32_e32 v0, 0xbfb8aa3b, v167
	v_exp_f32_e32 v0, v0
	v_lshlrev_b32_e32 v167, 16, v173
	v_add_f32_e32 v0, 1.0, v0
	v_rcp_f32_e32 v0, v0
	s_nop 0
	v_fmac_f32_e32 v175, v32, v0
	v_mul_f32_e32 v0, 0xbfb8aa3b, v155
	v_exp_f32_e32 v0, v0
	s_nop 0
	v_add_f32_e32 v0, 1.0, v0
	v_rcp_f32_e32 v0, v0
	s_nop 0
	v_fmac_f32_e32 v159, v37, v0
	v_mul_f32_e32 v0, 0xbfb8aa3b, v157
	v_exp_f32_e32 v0, v0
	v_cvt_pk_bf16_f32 v155, v169, v159
	v_lshlrev_b64 v[158:159], 11, v[164:165]
	v_cvt_pk_bf16_f32 v156, v174, v160
	v_add_f32_e32 v0, 1.0, v0
	v_rcp_f32_e32 v0, v0
	v_lshl_add_u64 v[158:159], v[162:163], 0, v[158:159]
	v_lshlrev_b32_e32 v165, 16, v172
	v_and_b32_e32 v160, 0xffff0000, v170
	v_fmac_f32_e32 v161, v33, v0
	v_lshlrev_b32_e32 v0, 16, v150
	v_mul_f32_e32 v0, 0xbfb8aa3b, v0
	v_exp_f32_e32 v0, v0
	v_cvt_pk_bf16_f32 v157, v175, v161
	global_store_dwordx4 v[158:159], v[154:157], off
	v_and_b32_e32 v150, 0xffff0000, v150
	v_add_f32_e32 v0, 1.0, v0
	v_rcp_f32_e32 v0, v0
	v_lshlrev_b32_e32 v155, 16, v152
	v_lshlrev_b32_e32 v157, 16, v170
	v_and_b32_e32 v152, 0xffff0000, v152
	v_fmac_f32_e32 v157, v26, v0
	v_mul_f32_e32 v0, 0xbfb8aa3b, v155
	v_exp_f32_e32 v0, v0
	v_lshlrev_b32_e32 v154, 16, v151
	v_lshlrev_b32_e32 v156, 16, v153
	v_lshlrev_b32_e32 v161, 16, v171
	v_add_f32_e32 v0, 1.0, v0
	v_rcp_f32_e32 v0, v0
	v_and_b32_e32 v151, 0xffff0000, v151
	v_and_b32_e32 v153, 0xffff0000, v153
	v_and_b32_e32 v164, 0xffff0000, v171
	v_fmac_f32_e32 v165, v22, v0
	v_mul_f32_e32 v0, 0xbfb8aa3b, v150
	v_exp_f32_e32 v0, v0
	v_lshlrev_b32_e32 v155, 16, v143
	v_and_b32_e32 v143, 0xffff0000, v143
	v_add_f32_e32 v0, 1.0, v0
	v_rcp_f32_e32 v0, v0
	s_nop 0
	v_fmac_f32_e32 v160, v27, v0
	v_mul_f32_e32 v0, 0xbfb8aa3b, v152
	v_exp_f32_e32 v0, v0
	v_cvt_pk_bf16_f32 v150, v157, v160
	v_lshlrev_b32_e32 v157, 16, v145
	v_and_b32_e32 v145, 0xffff0000, v145
; __device__ __forceinline__ float sigmoidf_(float g) { return __builtin_amdgcn_rcpf(1.f + __expf(-g)); }
; __device__ __forceinline__ u32x4 pack8(const f32x4& a, const f32x4& b) { u32x4 w; w.x = cvt_pk_bf16(a[0], a[1]); w.y = cvt_pk_bf16(a[2], a[3]); w.z = cvt_pk_bf16(b[0], b[1]); w.w = cvt_pk_bf16(b[2], b[3]); return w; }
; __device__ __forceinline__ void unpack8(const u32x4& w, float (&v)[8]) { v[0] = bf_lo(w.x); v[1] = bf_hi(w.x); v[2] = bf_lo(w.y); v[3] = bf_hi(w.y); v[4] = bf_lo(w.z); v[5] = bf_hi(w.z); v[6] = bf_lo(w.w); v[7] = bf_hi(w.w); }
;     __device__ __forceinline__ void apply(const Ld& d, int row, int c0, int, int, int, const f32x4& a0, const f32x4& b0, const f32x4& a1, const f32x4& b1) const { half(d.g0, row, c0, a0, b0); half(d.g1, row, c0 + 128, a1, b1); }
;     __device__ __forceinline__ void operator()(const f32x4 (&acc)[2][2][4][2], const Unit& u, int wr, int wc, int fr, int fq) const {
;         const int c0 = u.pn * BM + wc * 32 + 8 * fq;
; #pragma unroll
;         for (int ai = 0; ai < 2; ++ai)
; #pragma unroll
;             for (int mp = 0; mp < 4; mp += 2) {
;                 typename F::Ld ld[2];
; #pragma unroll
;                 for (int m = 0; m < 2; ++m) f.load(ld[m], u.pm * BM + ai * HALF + wr * 64 + (mp + m) * 16 + fr, c0, u.pn, fq);
; #pragma unroll
;                 for (int m = 0; m < 2; ++m) f.apply(ld[m], u.pm * BM + ai * HALF + wr * 64 + (mp + m) * 16 + fr, c0, u.pn, wc, fq, acc[ai][0][mp + m][0], acc[ai][0][mp + m][1], acc[ai][1][mp + m][0], acc[ai][1][mp + m][1]);
;             }
;     }
;     __device__ __forceinline__ void half(const u32x4& gw, const u32x4& pw, int row, int col, const f32x4& a, const f32x4& b) const {
;         float g[8]; unpack8(gw, g); float p[8]; unpack8(pw, p);
;         f32x4 r0, r1;
; #pragma unroll
;         for (int i = 0; i < 4; ++i) { r0[i] = a[i] * sigmoidf_(g[i]) + p[i]; r1[i] = b[i] * sigmoidf_(g[4 + i]) + p[4 + i]; }
;         *(u32x4*)(merged + (size_t)row * 1024 + col) = pack8(r0, r1);
;     }
;     __device__ __forceinline__ void apply(const Ld& d, int row, int c0, int, int, int, const f32x4& a0, const f32x4& b0, const f32x4& a1, const f32x4& b1) const { half(d.g0, d.p0, row, c0, a0, b0); half(d.g1, d.p1, row, c0 + 128, a1, b1); }
	v_add_f32_e32 v0, 1.0, v0
	v_rcp_f32_e32 v0, v0
	s_nop 0
	v_fmac_f32_e32 v166, v23, v0
	v_mul_f32_e32 v0, 0xbfb8aa3b, v154
	v_exp_f32_e32 v0, v0
	v_lshlrev_b32_e32 v154, 16, v142
	v_and_b32_e32 v142, 0xffff0000, v142
	v_add_f32_e32 v0, 1.0, v0
	v_rcp_f32_e32 v0, v0
	s_nop 0
	v_fmac_f32_e32 v161, v28, v0
	v_mul_f32_e32 v0, 0xbfb8aa3b, v156
	v_exp_f32_e32 v0, v0
	v_lshlrev_b32_e32 v156, 16, v144
	v_and_b32_e32 v144, 0xffff0000, v144
	v_add_f32_e32 v0, 1.0, v0
	v_rcp_f32_e32 v0, v0
	s_nop 0
	v_fmac_f32_e32 v167, v24, v0
	v_mul_f32_e32 v0, 0xbfb8aa3b, v151
	v_exp_f32_e32 v0, v0
	s_nop 0
	v_add_f32_e32 v0, 1.0, v0
	v_rcp_f32_e32 v0, v0
	s_nop 0
	v_fmac_f32_e32 v164, v29, v0
	v_mul_f32_e32 v0, 0xbfb8aa3b, v153
	v_exp_f32_e32 v0, v0
	v_cvt_pk_bf16_f32 v151, v161, v164
	v_cvt_pk_bf16_f32 v152, v165, v166
	s_nop 0
	v_add_f32_e32 v0, 1.0, v0
	v_rcp_f32_e32 v0, v0
	s_nop 0
	v_fmac_f32_e32 v168, v25, v0
	v_lshlrev_b32_e32 v0, 16, v146
	v_mul_f32_e32 v0, 0xbfb8aa3b, v0
	v_exp_f32_e32 v0, v0
	v_cvt_pk_bf16_f32 v153, v167, v168
	global_store_dwordx4 v[158:159], v[150:153], off offset:256
	v_and_b32_e32 v146, 0xffff0000, v146
	v_add_f32_e32 v0, 1.0, v0
	v_rcp_f32_e32 v0, v0
	v_lshlrev_b32_e32 v152, 16, v148
	v_and_b32_e32 v148, 0xffff0000, v148
	v_lshlrev_b32_e32 v151, 16, v147
	v_fmac_f32_e32 v154, v18, v0
	v_mul_f32_e32 v0, 0xbfb8aa3b, v152
	v_exp_f32_e32 v0, v0
	v_lshlrev_b32_e32 v153, 16, v149
	v_and_b32_e32 v147, 0xffff0000, v147
	v_and_b32_e32 v149, 0xffff0000, v149
	v_add_f32_e32 v0, 1.0, v0
	v_rcp_f32_e32 v0, v0
	v_add_u32_e32 v150, s0, v240
	v_fmac_f32_e32 v156, v10, v0
	v_mul_f32_e32 v0, 0xbfb8aa3b, v146
	v_exp_f32_e32 v0, v0
	s_nop 0
	v_add_f32_e32 v0, 1.0, v0
	v_rcp_f32_e32 v0, v0
	s_nop 0
	v_fmac_f32_e32 v142, v19, v0
	v_mul_f32_e32 v0, 0xbfb8aa3b, v148
	v_exp_f32_e32 v0, v0
	v_cvt_pk_bf16_f32 v142, v154, v142
	v_lshlrev_b32_e32 v148, 16, v135
	v_and_b32_e32 v135, 0xffff0000, v135
	v_add_f32_e32 v0, 1.0, v0
	v_rcp_f32_e32 v0, v0
	s_nop 0
	v_fmac_f32_e32 v144, v11, v0
	v_mul_f32_e32 v0, 0xbfb8aa3b, v151
	v_exp_f32_e32 v0, v0
	v_ashrrev_i32_e32 v151, 31, v150
	v_add_f32_e32 v0, 1.0, v0
	v_rcp_f32_e32 v0, v0
	s_nop 0
	v_fmac_f32_e32 v155, v20, v0
	v_mul_f32_e32 v0, 0xbfb8aa3b, v153
	v_exp_f32_e32 v0, v0
	s_nop 0
	v_add_f32_e32 v0, 1.0, v0
	v_rcp_f32_e32 v0, v0
	s_nop 0
	v_fmac_f32_e32 v157, v12, v0
	v_mul_f32_e32 v0, 0xbfb8aa3b, v147
	v_exp_f32_e32 v0, v0
	v_lshlrev_b64 v[146:147], 11, v[150:151]
	v_lshl_add_u64 v[146:147], v[162:163], 0, v[146:147]
	v_lshlrev_b32_e32 v150, 16, v137
	v_add_f32_e32 v0, 1.0, v0
	v_rcp_f32_e32 v0, v0
	v_and_b32_e32 v137, 0xffff0000, v137
	v_fmac_f32_e32 v143, v21, v0
	v_mul_f32_e32 v0, 0xbfb8aa3b, v149
	v_exp_f32_e32 v0, v0
	v_cvt_pk_bf16_f32 v143, v155, v143
	v_cvt_pk_bf16_f32 v144, v156, v144
	v_lshlrev_b32_e32 v149, 16, v136
	v_add_f32_e32 v0, 1.0, v0
	v_rcp_f32_e32 v0, v0
	v_and_b32_e32 v136, 0xffff0000, v136
	v_fmac_f32_e32 v145, v13, v0
	v_lshlrev_b32_e32 v0, 16, v138
	v_mul_f32_e32 v0, 0xbfb8aa3b, v0
	v_exp_f32_e32 v0, v0
	v_cvt_pk_bf16_f32 v145, v157, v145
	global_store_dwordx4 v[146:147], v[142:145], off
	v_and_b32_e32 v138, 0xffff0000, v138
	v_add_f32_e32 v0, 1.0, v0
	v_rcp_f32_e32 v0, v0
	v_lshlrev_b32_e32 v143, 16, v140
	v_lshlrev_b32_e32 v145, 16, v134
	v_and_b32_e32 v140, 0xffff0000, v140
	v_fmac_f32_e32 v145, v6, v0
	v_mul_f32_e32 v0, 0xbfb8aa3b, v143
	v_exp_f32_e32 v0, v0
	v_and_b32_e32 v134, 0xffff0000, v134
	v_lshlrev_b32_e32 v142, 16, v139
	v_lshlrev_b32_e32 v144, 16, v141
	v_add_f32_e32 v0, 1.0, v0
	v_rcp_f32_e32 v0, v0
	v_and_b32_e32 v139, 0xffff0000, v139
	v_and_b32_e32 v141, 0xffff0000, v141
	v_fmac_f32_e32 v149, v2, v0
	v_mul_f32_e32 v0, 0xbfb8aa3b, v138
	v_exp_f32_e32 v0, v0
	s_nop 0
	v_add_f32_e32 v0, 1.0, v0
	v_rcp_f32_e32 v0, v0
	s_nop 0
	v_fmac_f32_e32 v134, v7, v0
	v_mul_f32_e32 v0, 0xbfb8aa3b, v140
	v_exp_f32_e32 v0, v0
	v_cvt_pk_bf16_f32 v134, v145, v134
	s_nop 0
	v_add_f32_e32 v0, 1.0, v0
	v_rcp_f32_e32 v0, v0
	s_nop 0
	v_fmac_f32_e32 v136, v3, v0
	v_mul_f32_e32 v0, 0xbfb8aa3b, v142
	v_exp_f32_e32 v0, v0
	s_nop 0
	v_add_f32_e32 v0, 1.0, v0
	v_rcp_f32_e32 v0, v0
	s_nop 0
	v_fmac_f32_e32 v148, v8, v0
	v_mul_f32_e32 v0, 0xbfb8aa3b, v144
	v_exp_f32_e32 v0, v0
	s_nop 0
	v_add_f32_e32 v0, 1.0, v0
	v_rcp_f32_e32 v0, v0
	s_nop 0
	v_fmac_f32_e32 v150, v4, v0
	v_mul_f32_e32 v0, 0xbfb8aa3b, v139
	v_exp_f32_e32 v0, v0
	s_nop 0
	v_add_f32_e32 v0, 1.0, v0
	v_rcp_f32_e32 v0, v0
	s_nop 0
	v_fmac_f32_e32 v135, v9, v0
	v_mul_f32_e32 v0, 0xbfb8aa3b, v141
	v_exp_f32_e32 v0, v0
	v_cvt_pk_bf16_f32 v135, v148, v135
	v_cvt_pk_bf16_f32 v136, v149, v136
	s_nop 0
	v_add_f32_e32 v0, 1.0, v0
	v_rcp_f32_e32 v0, v0
	s_nop 0
	v_fmac_f32_e32 v137, v5, v0
	v_cvt_pk_bf16_f32 v137, v150, v137
	global_store_dwordx4 v[146:147], v[134:137], off offset:256

; __device__ __forceinline__ float sigmoidf_(float g) { return __builtin_amdgcn_rcpf(1.f + __expf(-g)); }
; __device__ __forceinline__ u32x4 pack8(const f32x4& a, const f32x4& b) { u32x4 w; w.x = cvt_pk_bf16(a[0], a[1]); w.y = cvt_pk_bf16(a[2], a[3]); w.z = cvt_pk_bf16(b[0], b[1]); w.w = cvt_pk_bf16(b[2], b[3]); return w; }
; __device__ __forceinline__ void unpack8(const u32x4& w, float (&v)[8]) { v[0] = bf_lo(w.x); v[1] = bf_hi(w.x); v[2] = bf_lo(w.y); v[3] = bf_hi(w.y); v[4] = bf_lo(w.z); v[5] = bf_hi(w.z); v[6] = bf_lo(w.w); v[7] = bf_hi(w.w); }
;     __device__ __forceinline__ void apply(const Ld& d, int row, int c0, int, int, int, const f32x4& a0, const f32x4& b0, const f32x4& a1, const f32x4& b1) const { half(d.g0, d.p0, row, c0, a0, b0); half(d.g1, d.p1, row, c0 + 128, a1, b1); }
;     __device__ __forceinline__ void operator()(const f32x4 (&acc)[2][2][4][2], const Unit& u, int wr, int wc, int fr, int fq) const {
;         const int c0 = u.pn * BM + wc * 32 + 8 * fq;
; #pragma unroll
;         for (int ai = 0; ai < 2; ++ai)
; #pragma unroll
;             for (int mp = 0; mp < 4; mp += 2) {
;                 typename F::Ld ld[2];
; #pragma unroll
;                 for (int m = 0; m < 2; ++m) f.load(ld[m], u.pm * BM + ai * HALF + wr * 64 + (mp + m) * 16 + fr, c0, u.pn, fq);
; #pragma unroll
;                 for (int m = 0; m < 2; ++m) f.apply(ld[m], u.pm * BM + ai * HALF + wr * 64 + (mp + m) * 16 + fr, c0, u.pn, wc, fq, acc[ai][0][mp + m][0], acc[ai][0][mp + m][1], acc[ai][1][mp + m][0], acc[ai][1][mp + m][1]);
;             }
;     }
;     __device__ __forceinline__ void half(const u32x4& gw, int row, int col, const f32x4& a, const f32x4& b) const {
;         float g[8]; unpack8(gw, g);
;         f32x4 r0, r1;
; #pragma unroll
;         for (int i = 0; i < 4; ++i) { r0[i] = a[i] * sigmoidf_(g[i]); r1[i] = b[i] * sigmoidf_(g[4 + i]); }
;         *(u32x4*)(proj + (size_t)row * PW + C_MPOOL + col) = pack8(r0, r1);
;     }
;     __device__ __forceinline__ void apply(const Ld& d, int row, int c0, int, int, int, const f32x4& a0, const f32x4& b0, const f32x4& a1, const f32x4& b1) const { half(d.g0, row, c0, a0, b0); half(d.g1, row, c0 + 128, a1, b1); }
.LBB0_286:
	s_andn2_b64 vcc, exec, s[0:1]
	s_cbranch_vccnz .LBB0_288
	v_lshl_or_b32 v134, s71, 8, v241
	v_ashrrev_i32_e32 v135, 31, v134
	v_lshl_add_u32 v0, s63, 8, v17
	v_mov_b64_e32 v[146:147], s[74:75]
	v_mad_i64_i32 v[136:137], s[0:1], v0, s29, v[146:147]
	v_lshlrev_b64 v[148:149], 1, v[134:135]
	v_lshl_add_u64 v[152:153], v[136:137], 0, v[148:149]
	v_add_co_u32_e32 v134, vcc, 0x1000, v152
	s_nop 1
	v_addc_co_u32_e32 v135, vcc, 0, v153, vcc
	global_load_dwordx4 v[154:157], v[134:135], off offset:1024
	global_load_dwordx4 v[142:145], v[134:135], off offset:1280
	v_or_b32_e32 v134, 16, v0
	v_mad_i64_i32 v[134:135], s[0:1], v134, s29, v[146:147]
	v_lshl_add_u64 v[150:151], v[134:135], 0, v[148:149]
	v_add_co_u32_e32 v134, vcc, 0x1000, v150
	s_waitcnt vmcnt(0)
	v_lshlrev_b32_e32 v158, 16, v154
	v_addc_co_u32_e32 v135, vcc, 0, v151, vcc
	global_load_dwordx4 v[138:141], v[134:135], off offset:1024
	s_nop 0
	global_load_dwordx4 v[134:137], v[134:135], off offset:1280
	v_and_b32_e32 v154, 0xffff0000, v154
	v_lshlrev_b32_e32 v159, 16, v155
	v_and_b32_e32 v155, 0xffff0000, v155
	v_lshlrev_b32_e32 v160, 16, v156
	v_and_b32_e32 v156, 0xffff0000, v156
	v_lshlrev_b32_e32 v161, 16, v157
	v_and_b32_e32 v157, 0xffff0000, v157
	v_mul_f32_e32 v154, 0xbfb8aa3b, v154
	v_mul_f32_e32 v158, 0xbfb8aa3b, v158
	v_exp_f32_e32 v154, v154
	v_mul_f32_e32 v156, 0xbfb8aa3b, v156
	v_mul_f32_e32 v155, 0xbfb8aa3b, v155
	v_mul_f32_e32 v157, 0xbfb8aa3b, v157
	v_exp_f32_e32 v158, v158
	v_mul_f32_e32 v160, 0xbfb8aa3b, v160
	v_exp_f32_e32 v156, v156
	v_mul_f32_e32 v159, 0xbfb8aa3b, v159
	v_mul_f32_e32 v161, 0xbfb8aa3b, v161
	v_exp_f32_e32 v155, v155
	v_exp_f32_e32 v157, v157
	v_exp_f32_e32 v160, v160
	v_exp_f32_e32 v159, v159
	v_exp_f32_e32 v161, v161
	v_add_f32_e32 v154, 1.0, v154
	v_add_f32_e32 v158, 1.0, v158
	v_rcp_f32_e32 v154, v154
	v_add_f32_e32 v156, 1.0, v156
	v_add_f32_e32 v155, 1.0, v155
	v_add_f32_e32 v157, 1.0, v157
	v_rcp_f32_e32 v158, v158
	v_add_f32_e32 v160, 1.0, v160
	v_rcp_f32_e32 v156, v156
	v_add_f32_e32 v159, 1.0, v159
	v_add_f32_e32 v161, 1.0, v161
	v_rcp_f32_e32 v155, v155
	v_rcp_f32_e32 v157, v157
	v_rcp_f32_e32 v160, v160
	v_rcp_f32_e32 v159, v159
	v_rcp_f32_e32 v161, v161
	v_mul_f32_e32 v154, v131, v154
	v_mul_f32_e32 v158, v130, v158
	v_mul_f32_e32 v156, v127, v156
	v_mul_f32_e32 v155, v133, v155
	v_mul_f32_e32 v157, v129, v157
	v_cvt_pk_bf16_f32 v154, v158, v154
	v_mul_f32_e32 v160, v126, v160
	v_mul_f32_e32 v159, v132, v159
	v_mul_f32_e32 v161, v128, v161
	v_cvt_pk_bf16_f32 v155, v159, v155
	v_cvt_pk_bf16_f32 v156, v160, v156
	v_cvt_pk_bf16_f32 v157, v161, v157
	global_store_dwordx4 v[152:153], v[154:157], off offset:2048
	s_nop 1
	v_lshlrev_b32_e32 v154, 16, v142
	v_and_b32_e32 v142, 0xffff0000, v142
	v_lshlrev_b32_e32 v155, 16, v143
	v_and_b32_e32 v143, 0xffff0000, v143
	v_lshlrev_b32_e32 v156, 16, v144
	v_and_b32_e32 v144, 0xffff0000, v144
	v_lshlrev_b32_e32 v157, 16, v145
	v_and_b32_e32 v145, 0xffff0000, v145
	v_mul_f32_e32 v142, 0xbfb8aa3b, v142
	v_mul_f32_e32 v154, 0xbfb8aa3b, v154
	v_exp_f32_e32 v142, v142
	v_mul_f32_e32 v144, 0xbfb8aa3b, v144
	v_mul_f32_e32 v143, 0xbfb8aa3b, v143
	v_mul_f32_e32 v145, 0xbfb8aa3b, v145
	v_exp_f32_e32 v154, v154
	v_mul_f32_e32 v156, 0xbfb8aa3b, v156
	v_exp_f32_e32 v144, v144
	v_mul_f32_e32 v155, 0xbfb8aa3b, v155
	v_mul_f32_e32 v157, 0xbfb8aa3b, v157
	v_exp_f32_e32 v143, v143
	v_exp_f32_e32 v145, v145
	v_exp_f32_e32 v156, v156
	v_exp_f32_e32 v155, v155
	v_exp_f32_e32 v157, v157
	v_add_f32_e32 v142, 1.0, v142
	v_add_f32_e32 v154, 1.0, v154
	v_rcp_f32_e32 v142, v142
	v_add_f32_e32 v144, 1.0, v144
	v_add_f32_e32 v143, 1.0, v143
	v_add_f32_e32 v145, 1.0, v145
	v_rcp_f32_e32 v154, v154
	v_add_f32_e32 v156, 1.0, v156
	v_rcp_f32_e32 v144, v144
	v_add_f32_e32 v155, 1.0, v155
	v_add_f32_e32 v157, 1.0, v157
	v_rcp_f32_e32 v143, v143
	v_rcp_f32_e32 v145, v145
	v_rcp_f32_e32 v156, v156
	v_rcp_f32_e32 v155, v155
	v_rcp_f32_e32 v157, v157
	v_mul_f32_e32 v142, v123, v142
	v_mul_f32_e32 v154, v122, v154
	v_mul_f32_e32 v144, v119, v144
	v_mul_f32_e32 v143, v125, v143
	v_mul_f32_e32 v145, v121, v145
	v_cvt_pk_bf16_f32 v142, v154, v142
	v_mul_f32_e32 v156, v118, v156
	v_mul_f32_e32 v155, v124, v155
	v_mul_f32_e32 v157, v120, v157
	v_cvt_pk_bf16_f32 v143, v155, v143
	v_cvt_pk_bf16_f32 v144, v156, v144
	v_cvt_pk_bf16_f32 v145, v157, v145
	global_store_dwordx4 v[152:153], v[142:145], off offset:2304
	s_waitcnt vmcnt(2)
; __device__ __forceinline__ float sigmoidf_(float g) { return __builtin_amdgcn_rcpf(1.f + __expf(-g)); }
; __device__ __forceinline__ u32x4 pack8(const f32x4& a, const f32x4& b) { u32x4 w; w.x = cvt_pk_bf16(a[0], a[1]); w.y = cvt_pk_bf16(a[2], a[3]); w.z = cvt_pk_bf16(b[0], b[1]); w.w = cvt_pk_bf16(b[2], b[3]); return w; }
; __device__ __forceinline__ void unpack8(const u32x4& w, float (&v)[8]) { v[0] = bf_lo(w.x); v[1] = bf_hi(w.x); v[2] = bf_lo(w.y); v[3] = bf_hi(w.y); v[4] = bf_lo(w.z); v[5] = bf_hi(w.z); v[6] = bf_lo(w.w); v[7] = bf_hi(w.w); }
;     __device__ __forceinline__ void apply(const Ld& d, int row, int c0, int, int, int, const f32x4& a0, const f32x4& b0, const f32x4& a1, const f32x4& b1) const { half(d.g0, d.p0, row, c0, a0, b0); half(d.g1, d.p1, row, c0 + 128, a1, b1); }
;     __device__ __forceinline__ void operator()(const f32x4 (&acc)[2][2][4][2], const Unit& u, int wr, int wc, int fr, int fq) const {
;         const int c0 = u.pn * BM + wc * 32 + 8 * fq;
; #pragma unroll
;         for (int ai = 0; ai < 2; ++ai)
; #pragma unroll
;             for (int mp = 0; mp < 4; mp += 2) {
;                 typename F::Ld ld[2];
; #pragma unroll
;                 for (int m = 0; m < 2; ++m) f.load(ld[m], u.pm * BM + ai * HALF + wr * 64 + (mp + m) * 16 + fr, c0, u.pn, fq);
; #pragma unroll
;                 for (int m = 0; m < 2; ++m) f.apply(ld[m], u.pm * BM + ai * HALF + wr * 64 + (mp + m) * 16 + fr, c0, u.pn, wc, fq, acc[ai][0][mp + m][0], acc[ai][0][mp + m][1], acc[ai][1][mp + m][0], acc[ai][1][mp + m][1]);
;             }
;     }
;     __device__ __forceinline__ void half(const u32x4& gw, int row, int col, const f32x4& a, const f32x4& b) const {
;         float g[8]; unpack8(gw, g);
;         f32x4 r0, r1;
; #pragma unroll
;         for (int i = 0; i < 4; ++i) { r0[i] = a[i] * sigmoidf_(g[i]); r1[i] = b[i] * sigmoidf_(g[4 + i]); }
;         *(u32x4*)(proj + (size_t)row * PW + C_MPOOL + col) = pack8(r0, r1);
;     }
;     __device__ __forceinline__ void apply(const Ld& d, int row, int c0, int, int, int, const f32x4& a0, const f32x4& b0, const f32x4& a1, const f32x4& b1) const { half(d.g0, row, c0, a0, b0); half(d.g1, row, c0 + 128, a1, b1); }
	s_nop 0
	v_lshlrev_b32_e32 v142, 16, v138
	v_and_b32_e32 v138, 0xffff0000, v138
	v_lshlrev_b32_e32 v143, 16, v139
	v_and_b32_e32 v139, 0xffff0000, v139
	v_lshlrev_b32_e32 v144, 16, v140
	v_and_b32_e32 v140, 0xffff0000, v140
	v_lshlrev_b32_e32 v145, 16, v141
	v_and_b32_e32 v141, 0xffff0000, v141
	v_mul_f32_e32 v138, 0xbfb8aa3b, v138
	v_mul_f32_e32 v142, 0xbfb8aa3b, v142
	v_exp_f32_e32 v138, v138
	v_mul_f32_e32 v140, 0xbfb8aa3b, v140
	v_mul_f32_e32 v139, 0xbfb8aa3b, v139
	v_mul_f32_e32 v141, 0xbfb8aa3b, v141
	v_exp_f32_e32 v142, v142
	v_mul_f32_e32 v144, 0xbfb8aa3b, v144
	v_exp_f32_e32 v140, v140
	v_mul_f32_e32 v143, 0xbfb8aa3b, v143
	v_mul_f32_e32 v145, 0xbfb8aa3b, v145
	v_exp_f32_e32 v139, v139
	v_exp_f32_e32 v141, v141
	v_exp_f32_e32 v144, v144
	v_exp_f32_e32 v143, v143
	v_exp_f32_e32 v145, v145
	v_add_f32_e32 v138, 1.0, v138
	v_add_f32_e32 v142, 1.0, v142
	v_rcp_f32_e32 v138, v138
	v_add_f32_e32 v140, 1.0, v140
	v_add_f32_e32 v139, 1.0, v139
	v_add_f32_e32 v141, 1.0, v141
	v_rcp_f32_e32 v142, v142
	v_add_f32_e32 v144, 1.0, v144
	v_rcp_f32_e32 v140, v140
	v_add_f32_e32 v143, 1.0, v143
	v_add_f32_e32 v145, 1.0, v145
	v_rcp_f32_e32 v139, v139
	v_rcp_f32_e32 v141, v141
	v_rcp_f32_e32 v144, v144
	v_rcp_f32_e32 v143, v143
	v_rcp_f32_e32 v145, v145
	v_mul_f32_e32 v138, v115, v138
	v_mul_f32_e32 v142, v114, v142
	v_mul_f32_e32 v140, v111, v140
	v_mul_f32_e32 v139, v117, v139
	v_mul_f32_e32 v141, v113, v141
	v_cvt_pk_bf16_f32 v138, v142, v138
	v_mul_f32_e32 v144, v110, v144
	v_mul_f32_e32 v143, v116, v143
	v_mul_f32_e32 v145, v112, v145
	v_cvt_pk_bf16_f32 v139, v143, v139
	v_cvt_pk_bf16_f32 v140, v144, v140
	v_cvt_pk_bf16_f32 v141, v145, v141
	global_store_dwordx4 v[150:151], v[138:141], off offset:2048
	s_nop 1
	v_lshlrev_b32_e32 v138, 16, v134
	v_and_b32_e32 v134, 0xffff0000, v134
	v_lshlrev_b32_e32 v139, 16, v135
	v_and_b32_e32 v135, 0xffff0000, v135
	v_lshlrev_b32_e32 v140, 16, v136
	v_and_b32_e32 v136, 0xffff0000, v136
	v_lshlrev_b32_e32 v141, 16, v137
	v_and_b32_e32 v137, 0xffff0000, v137
	v_mul_f32_e32 v134, 0xbfb8aa3b, v134
	v_mul_f32_e32 v138, 0xbfb8aa3b, v138
	v_exp_f32_e32 v134, v134
	v_mul_f32_e32 v136, 0xbfb8aa3b, v136
	v_mul_f32_e32 v135, 0xbfb8aa3b, v135
	v_mul_f32_e32 v137, 0xbfb8aa3b, v137
	v_exp_f32_e32 v138, v138
	v_mul_f32_e32 v140, 0xbfb8aa3b, v140
	v_exp_f32_e32 v136, v136
	v_mul_f32_e32 v139, 0xbfb8aa3b, v139
	v_mul_f32_e32 v141, 0xbfb8aa3b, v141
	v_exp_f32_e32 v135, v135
	v_exp_f32_e32 v137, v137
	v_exp_f32_e32 v140, v140
	v_exp_f32_e32 v139, v139
	v_exp_f32_e32 v141, v141
	v_add_f32_e32 v134, 1.0, v134
	v_add_f32_e32 v138, 1.0, v138
	v_rcp_f32_e32 v134, v134
	v_add_f32_e32 v136, 1.0, v136
	v_add_f32_e32 v135, 1.0, v135
	v_add_f32_e32 v137, 1.0, v137
	v_rcp_f32_e32 v138, v138
	v_add_f32_e32 v140, 1.0, v140
	v_rcp_f32_e32 v136, v136
	v_add_f32_e32 v139, 1.0, v139
	v_add_f32_e32 v141, 1.0, v141
	v_rcp_f32_e32 v135, v135
	v_rcp_f32_e32 v137, v137
	v_rcp_f32_e32 v140, v140
	v_rcp_f32_e32 v139, v139
	v_rcp_f32_e32 v141, v141
	v_mul_f32_e32 v134, v107, v134
	v_mul_f32_e32 v138, v106, v138
	v_mul_f32_e32 v136, v103, v136
	v_mul_f32_e32 v135, v109, v135
	v_mul_f32_e32 v137, v105, v137
	v_cvt_pk_bf16_f32 v134, v138, v134
	v_mul_f32_e32 v140, v102, v140
	v_mul_f32_e32 v139, v108, v139
	v_mul_f32_e32 v141, v104, v141
	v_cvt_pk_bf16_f32 v135, v139, v135
	v_cvt_pk_bf16_f32 v136, v140, v136
	v_cvt_pk_bf16_f32 v137, v141, v137
	global_store_dwordx4 v[150:151], v[134:137], off offset:2304
	s_nop 1
	v_or_b32_e32 v134, 32, v0
	v_mad_i64_i32 v[134:135], s[0:1], v134, s29, v[146:147]
	v_lshl_add_u64 v[144:145], v[134:135], 0, v[148:149]
	v_add_co_u32_e32 v134, vcc, s98, v144
	s_nop 1
	v_addc_co_u32_e32 v135, vcc, 0, v145, vcc
	global_load_dwordx4 v[150:153], v[134:135], off offset:1024
	global_load_dwordx4 v[154:157], v[134:135], off offset:1280
	v_or_b32_e32 v134, 48, v0
	v_mad_i64_i32 v[134:135], s[0:1], v134, s29, v[146:147]
	v_lshl_add_u64 v[142:143], v[134:135], 0, v[148:149]
	v_add_co_u32_e32 v134, vcc, s98, v142
	s_waitcnt vmcnt(0)
	v_lshlrev_b32_e32 v158, 16, v150
	v_addc_co_u32_e32 v135, vcc, 0, v143, vcc
	global_load_dwordx4 v[138:141], v[134:135], off offset:1024
	s_nop 0
	global_load_dwordx4 v[134:137], v[134:135], off offset:1280
	v_and_b32_e32 v150, 0xffff0000, v150
	v_lshlrev_b32_e32 v159, 16, v151
	v_and_b32_e32 v151, 0xffff0000, v151
	v_lshlrev_b32_e32 v160, 16, v152
	v_and_b32_e32 v152, 0xffff0000, v152
	v_lshlrev_b32_e32 v161, 16, v153
	v_and_b32_e32 v153, 0xffff0000, v153
	v_mul_f32_e32 v150, 0xbfb8aa3b, v150
	v_mul_f32_e32 v152, 0xbfb8aa3b, v152
	v_mul_f32_e32 v151, 0xbfb8aa3b, v151
	v_mul_f32_e32 v153, 0xbfb8aa3b, v153
	v_mul_f32_e32 v158, 0xbfb8aa3b, v158
	v_mul_f32_e32 v160, 0xbfb8aa3b, v160
	v_exp_f32_e32 v150, v150
	v_exp_f32_e32 v152, v152
	v_mul_f32_e32 v159, 0xbfb8aa3b, v159
	v_mul_f32_e32 v161, 0xbfb8aa3b, v161
	v_exp_f32_e32 v151, v151
	v_exp_f32_e32 v153, v153
	v_exp_f32_e32 v158, v158
	v_exp_f32_e32 v160, v160
	v_exp_f32_e32 v159, v159
	v_exp_f32_e32 v161, v161
	v_add_f32_e32 v150, 1.0, v150
	v_add_f32_e32 v152, 1.0, v152
	v_add_f32_e32 v151, 1.0, v151
	v_add_f32_e32 v153, 1.0, v153
	v_add_f32_e32 v158, 1.0, v158
	v_add_f32_e32 v160, 1.0, v160
	v_rcp_f32_e32 v150, v150
	v_rcp_f32_e32 v152, v152
	v_add_f32_e32 v159, 1.0, v159
	v_add_f32_e32 v161, 1.0, v161
	v_rcp_f32_e32 v151, v151
	v_rcp_f32_e32 v153, v153
	v_rcp_f32_e32 v158, v158
	v_rcp_f32_e32 v160, v160
	v_rcp_f32_e32 v159, v159
	v_rcp_f32_e32 v161, v161
	v_mul_f32_e32 v150, v99, v150
	v_mul_f32_e32 v152, v95, v152
	v_mul_f32_e32 v151, v101, v151
	v_mul_f32_e32 v153, v97, v153
	v_mul_f32_e32 v158, v98, v158
	v_mul_f32_e32 v160, v94, v160
; __device__ __forceinline__ float sigmoidf_(float g) { return __builtin_amdgcn_rcpf(1.f + __expf(-g)); }
; __device__ __forceinline__ u32x4 pack8(const f32x4& a, const f32x4& b) { u32x4 w; w.x = cvt_pk_bf16(a[0], a[1]); w.y = cvt_pk_bf16(a[2], a[3]); w.z = cvt_pk_bf16(b[0], b[1]); w.w = cvt_pk_bf16(b[2], b[3]); return w; }
; __device__ __forceinline__ void unpack8(const u32x4& w, float (&v)[8]) { v[0] = bf_lo(w.x); v[1] = bf_hi(w.x); v[2] = bf_lo(w.y); v[3] = bf_hi(w.y); v[4] = bf_lo(w.z); v[5] = bf_hi(w.z); v[6] = bf_lo(w.w); v[7] = bf_hi(w.w); }
;     __device__ __forceinline__ void apply(const Ld& d, int row, int c0, int, int, int, const f32x4& a0, const f32x4& b0, const f32x4& a1, const f32x4& b1) const { half(d.g0, d.p0, row, c0, a0, b0); half(d.g1, d.p1, row, c0 + 128, a1, b1); }
;     __device__ __forceinline__ void operator()(const f32x4 (&acc)[2][2][4][2], const Unit& u, int wr, int wc, int fr, int fq) const {
;         const int c0 = u.pn * BM + wc * 32 + 8 * fq;
; #pragma unroll
;         for (int ai = 0; ai < 2; ++ai)
; #pragma unroll
;             for (int mp = 0; mp < 4; mp += 2) {
;                 typename F::Ld ld[2];
; #pragma unroll
;                 for (int m = 0; m < 2; ++m) f.load(ld[m], u.pm * BM + ai * HALF + wr * 64 + (mp + m) * 16 + fr, c0, u.pn, fq);
; #pragma unroll
;                 for (int m = 0; m < 2; ++m) f.apply(ld[m], u.pm * BM + ai * HALF + wr * 64 + (mp + m) * 16 + fr, c0, u.pn, wc, fq, acc[ai][0][mp + m][0], acc[ai][0][mp + m][1], acc[ai][1][mp + m][0], acc[ai][1][mp + m][1]);
;             }
;     }
;     __device__ __forceinline__ void half(const u32x4& gw, int row, int col, const f32x4& a, const f32x4& b) const {
;         float g[8]; unpack8(gw, g);
;         f32x4 r0, r1;
; #pragma unroll
;         for (int i = 0; i < 4; ++i) { r0[i] = a[i] * sigmoidf_(g[i]); r1[i] = b[i] * sigmoidf_(g[4 + i]); }
;         *(u32x4*)(proj + (size_t)row * PW + C_MPOOL + col) = pack8(r0, r1);
;     }
;     __device__ __forceinline__ void apply(const Ld& d, int row, int c0, int, int, int, const f32x4& a0, const f32x4& b0, const f32x4& a1, const f32x4& b1) const { half(d.g0, row, c0, a0, b0); half(d.g1, row, c0 + 128, a1, b1); }
	v_mul_f32_e32 v159, v100, v159
	v_mul_f32_e32 v161, v96, v161
	v_cvt_pk_bf16_f32 v150, v158, v150
	v_cvt_pk_bf16_f32 v151, v159, v151
	v_cvt_pk_bf16_f32 v152, v160, v152
	v_cvt_pk_bf16_f32 v153, v161, v153
	global_store_dwordx4 v[144:145], v[150:153], off offset:2048
	s_nop 1
	v_lshlrev_b32_e32 v150, 16, v154
	v_and_b32_e32 v151, 0xffff0000, v154
	v_lshlrev_b32_e32 v152, 16, v155
	v_and_b32_e32 v153, 0xffff0000, v155
	v_lshlrev_b32_e32 v154, 16, v156
	v_and_b32_e32 v155, 0xffff0000, v156
	v_lshlrev_b32_e32 v156, 16, v157
	v_and_b32_e32 v157, 0xffff0000, v157
	v_mul_f32_e32 v150, 0xbfb8aa3b, v150
	v_mul_f32_e32 v151, 0xbfb8aa3b, v151
	v_mul_f32_e32 v152, 0xbfb8aa3b, v152
	v_mul_f32_e32 v153, 0xbfb8aa3b, v153
	v_exp_f32_e32 v150, v150
	v_mul_f32_e32 v154, 0xbfb8aa3b, v154
	v_exp_f32_e32 v151, v151
	v_mul_f32_e32 v155, 0xbfb8aa3b, v155
	v_exp_f32_e32 v152, v152
	v_mul_f32_e32 v156, 0xbfb8aa3b, v156
	v_exp_f32_e32 v153, v153
	v_mul_f32_e32 v157, 0xbfb8aa3b, v157
	v_exp_f32_e32 v154, v154
	v_exp_f32_e32 v155, v155
	v_exp_f32_e32 v156, v156
	v_exp_f32_e32 v157, v157
	v_add_f32_e32 v150, 1.0, v150
	v_add_f32_e32 v151, 1.0, v151
	v_add_f32_e32 v152, 1.0, v152
	v_add_f32_e32 v153, 1.0, v153
	v_rcp_f32_e32 v150, v150
	v_add_f32_e32 v154, 1.0, v154
	v_rcp_f32_e32 v151, v151
	v_add_f32_e32 v155, 1.0, v155
	v_rcp_f32_e32 v152, v152
	v_add_f32_e32 v156, 1.0, v156
	v_rcp_f32_e32 v153, v153
	v_add_f32_e32 v157, 1.0, v157
	v_rcp_f32_e32 v154, v154
	v_rcp_f32_e32 v155, v155
	v_rcp_f32_e32 v156, v156
	v_rcp_f32_e32 v157, v157
	v_mul_f32_e32 v150, v90, v150
	v_mul_f32_e32 v151, v91, v151
	v_mul_f32_e32 v152, v92, v152
	v_mul_f32_e32 v153, v93, v153
	v_mul_f32_e32 v154, v86, v154
	v_mul_f32_e32 v155, v87, v155
	v_mul_f32_e32 v156, v88, v156
	v_mul_f32_e32 v157, v89, v157
	v_cvt_pk_bf16_f32 v150, v150, v151
	v_cvt_pk_bf16_f32 v151, v152, v153
	v_cvt_pk_bf16_f32 v152, v154, v155
	v_cvt_pk_bf16_f32 v153, v156, v157
	global_store_dwordx4 v[144:145], v[150:153], off offset:2304
	s_waitcnt vmcnt(2)
	v_lshlrev_b32_e32 v144, 16, v138
	v_and_b32_e32 v138, 0xffff0000, v138
	v_lshlrev_b32_e32 v145, 16, v139
	v_and_b32_e32 v139, 0xffff0000, v139
	v_lshlrev_b32_e32 v150, 16, v140
	v_and_b32_e32 v140, 0xffff0000, v140
	v_lshlrev_b32_e32 v151, 16, v141
	v_and_b32_e32 v141, 0xffff0000, v141
	v_mul_f32_e32 v138, 0xbfb8aa3b, v138
	v_mul_f32_e32 v144, 0xbfb8aa3b, v144
	v_exp_f32_e32 v138, v138
	v_mul_f32_e32 v140, 0xbfb8aa3b, v140
	v_mul_f32_e32 v139, 0xbfb8aa3b, v139
	v_mul_f32_e32 v141, 0xbfb8aa3b, v141
	v_exp_f32_e32 v144, v144
	v_mul_f32_e32 v150, 0xbfb8aa3b, v150
	v_exp_f32_e32 v140, v140
	v_mul_f32_e32 v145, 0xbfb8aa3b, v145
	v_mul_f32_e32 v151, 0xbfb8aa3b, v151
	v_exp_f32_e32 v139, v139
	v_exp_f32_e32 v141, v141
	v_exp_f32_e32 v150, v150
	v_exp_f32_e32 v145, v145
	v_exp_f32_e32 v151, v151
	v_add_f32_e32 v138, 1.0, v138
	v_add_f32_e32 v144, 1.0, v144
	v_rcp_f32_e32 v138, v138
	v_add_f32_e32 v140, 1.0, v140
	v_add_f32_e32 v139, 1.0, v139
	v_add_f32_e32 v141, 1.0, v141
	v_rcp_f32_e32 v144, v144
	v_add_f32_e32 v150, 1.0, v150
	v_rcp_f32_e32 v140, v140
	v_add_f32_e32 v145, 1.0, v145
	v_add_f32_e32 v151, 1.0, v151
	v_rcp_f32_e32 v139, v139
	v_rcp_f32_e32 v141, v141
	v_rcp_f32_e32 v150, v150
	v_rcp_f32_e32 v145, v145
	v_rcp_f32_e32 v151, v151
	v_mul_f32_e32 v138, v83, v138
	v_mul_f32_e32 v144, v82, v144
	v_mul_f32_e32 v140, v79, v140
	v_mul_f32_e32 v139, v85, v139
	v_mul_f32_e32 v141, v81, v141
	v_cvt_pk_bf16_f32 v138, v144, v138
	v_mul_f32_e32 v150, v78, v150
	v_mul_f32_e32 v145, v84, v145
	v_mul_f32_e32 v151, v80, v151
	v_cvt_pk_bf16_f32 v139, v145, v139
	v_cvt_pk_bf16_f32 v140, v150, v140
	v_cvt_pk_bf16_f32 v141, v151, v141
	global_store_dwordx4 v[142:143], v[138:141], off offset:2048
	s_nop 1
	v_lshlrev_b32_e32 v138, 16, v134
	v_and_b32_e32 v134, 0xffff0000, v134
	v_lshlrev_b32_e32 v139, 16, v135
	v_and_b32_e32 v135, 0xffff0000, v135
	v_lshlrev_b32_e32 v140, 16, v136
	v_and_b32_e32 v136, 0xffff0000, v136
	v_lshlrev_b32_e32 v141, 16, v137
	v_and_b32_e32 v137, 0xffff0000, v137
	v_mul_f32_e32 v134, 0xbfb8aa3b, v134
	v_mul_f32_e32 v138, 0xbfb8aa3b, v138
	v_exp_f32_e32 v134, v134
	v_mul_f32_e32 v136, 0xbfb8aa3b, v136
	v_mul_f32_e32 v135, 0xbfb8aa3b, v135
	v_mul_f32_e32 v137, 0xbfb8aa3b, v137
	v_exp_f32_e32 v138, v138
	v_mul_f32_e32 v140, 0xbfb8aa3b, v140
	v_exp_f32_e32 v136, v136
	v_mul_f32_e32 v139, 0xbfb8aa3b, v139
	v_mul_f32_e32 v141, 0xbfb8aa3b, v141
	v_exp_f32_e32 v135, v135
	v_exp_f32_e32 v137, v137
	v_exp_f32_e32 v140, v140
	v_exp_f32_e32 v139, v139
	v_exp_f32_e32 v141, v141
	v_add_f32_e32 v134, 1.0, v134
	v_add_f32_e32 v138, 1.0, v138
	v_rcp_f32_e32 v134, v134
	v_add_f32_e32 v136, 1.0, v136
	v_add_f32_e32 v135, 1.0, v135
	v_add_f32_e32 v137, 1.0, v137
	v_rcp_f32_e32 v138, v138
	v_add_f32_e32 v140, 1.0, v140
	v_rcp_f32_e32 v136, v136
	v_add_f32_e32 v139, 1.0, v139
	v_add_f32_e32 v141, 1.0, v141
	v_rcp_f32_e32 v135, v135
	v_rcp_f32_e32 v137, v137
	v_rcp_f32_e32 v140, v140
	v_rcp_f32_e32 v139, v139
	v_rcp_f32_e32 v141, v141
	v_mul_f32_e32 v134, v75, v134
	v_mul_f32_e32 v138, v74, v138
	v_mul_f32_e32 v136, v71, v136
	v_mul_f32_e32 v135, v77, v135
	v_mul_f32_e32 v137, v73, v137
	v_cvt_pk_bf16_f32 v134, v138, v134
	v_mul_f32_e32 v140, v70, v140
	v_mul_f32_e32 v139, v76, v139
	v_mul_f32_e32 v141, v72, v141
	v_cvt_pk_bf16_f32 v135, v139, v135
	v_cvt_pk_bf16_f32 v136, v140, v136
	v_cvt_pk_bf16_f32 v137, v141, v137
	global_store_dwordx4 v[142:143], v[134:137], off offset:2304
	s_nop 1
	v_add_u32_e32 v134, 0x80, v0
	v_mad_i64_i32 v[134:135], s[0:1], v134, s29, v[146:147]
	v_lshl_add_u64 v[144:145], v[134:135], 0, v[148:149]
	v_add_co_u32_e32 v134, vcc, s98, v144
	s_nop 1
	v_addc_co_u32_e32 v135, vcc, 0, v145, vcc
	global_load_dwordx4 v[150:153], v[134:135], off offset:1024
	global_load_dwordx4 v[154:157], v[134:135], off offset:1280
	v_add_u32_e32 v134, 0x90, v0
	v_mad_i64_i32 v[134:135], s[0:1], v134, s29, v[146:147]
	v_lshl_add_u64 v[142:143], v[134:135], 0, v[148:149]
	v_add_co_u32_e32 v134, vcc, s98, v142
	s_waitcnt vmcnt(0)
; __device__ __forceinline__ float sigmoidf_(float g) { return __builtin_amdgcn_rcpf(1.f + __expf(-g)); }
; __device__ __forceinline__ u32x4 pack8(const f32x4& a, const f32x4& b) { u32x4 w; w.x = cvt_pk_bf16(a[0], a[1]); w.y = cvt_pk_bf16(a[2], a[3]); w.z = cvt_pk_bf16(b[0], b[1]); w.w = cvt_pk_bf16(b[2], b[3]); return w; }
; __device__ __forceinline__ void unpack8(const u32x4& w, float (&v)[8]) { v[0] = bf_lo(w.x); v[1] = bf_hi(w.x); v[2] = bf_lo(w.y); v[3] = bf_hi(w.y); v[4] = bf_lo(w.z); v[5] = bf_hi(w.z); v[6] = bf_lo(w.w); v[7] = bf_hi(w.w); }
;     __device__ __forceinline__ void apply(const Ld& d, int row, int c0, int, int, int, const f32x4& a0, const f32x4& b0, const f32x4& a1, const f32x4& b1) const { half(d.g0, d.p0, row, c0, a0, b0); half(d.g1, d.p1, row, c0 + 128, a1, b1); }
;     __device__ __forceinline__ void operator()(const f32x4 (&acc)[2][2][4][2], const Unit& u, int wr, int wc, int fr, int fq) const {
;         const int c0 = u.pn * BM + wc * 32 + 8 * fq;
; #pragma unroll
;         for (int ai = 0; ai < 2; ++ai)
; #pragma unroll
;             for (int mp = 0; mp < 4; mp += 2) {
;                 typename F::Ld ld[2];
; #pragma unroll
;                 for (int m = 0; m < 2; ++m) f.load(ld[m], u.pm * BM + ai * HALF + wr * 64 + (mp + m) * 16 + fr, c0, u.pn, fq);
; #pragma unroll
;                 for (int m = 0; m < 2; ++m) f.apply(ld[m], u.pm * BM + ai * HALF + wr * 64 + (mp + m) * 16 + fr, c0, u.pn, wc, fq, acc[ai][0][mp + m][0], acc[ai][0][mp + m][1], acc[ai][1][mp + m][0], acc[ai][1][mp + m][1]);
;             }
;     }
;     __device__ __forceinline__ void half(const u32x4& gw, int row, int col, const f32x4& a, const f32x4& b) const {
;         float g[8]; unpack8(gw, g);
;         f32x4 r0, r1;
; #pragma unroll
;         for (int i = 0; i < 4; ++i) { r0[i] = a[i] * sigmoidf_(g[i]); r1[i] = b[i] * sigmoidf_(g[4 + i]); }
;         *(u32x4*)(proj + (size_t)row * PW + C_MPOOL + col) = pack8(r0, r1);
;     }
;     __device__ __forceinline__ void apply(const Ld& d, int row, int c0, int, int, int, const f32x4& a0, const f32x4& b0, const f32x4& a1, const f32x4& b1) const { half(d.g0, row, c0, a0, b0); half(d.g1, row, c0 + 128, a1, b1); }
	v_lshlrev_b32_e32 v158, 16, v150
	v_addc_co_u32_e32 v135, vcc, 0, v143, vcc
	global_load_dwordx4 v[138:141], v[134:135], off offset:1024
	s_nop 0
	global_load_dwordx4 v[134:137], v[134:135], off offset:1280
	v_and_b32_e32 v150, 0xffff0000, v150
	v_lshlrev_b32_e32 v159, 16, v151
	v_and_b32_e32 v151, 0xffff0000, v151
	v_lshlrev_b32_e32 v160, 16, v152
	v_and_b32_e32 v152, 0xffff0000, v152
	v_lshlrev_b32_e32 v161, 16, v153
	v_and_b32_e32 v153, 0xffff0000, v153
	v_mul_f32_e32 v150, 0xbfb8aa3b, v150
	v_mul_f32_e32 v152, 0xbfb8aa3b, v152
	v_mul_f32_e32 v151, 0xbfb8aa3b, v151
	v_mul_f32_e32 v153, 0xbfb8aa3b, v153
	v_mul_f32_e32 v158, 0xbfb8aa3b, v158
	v_mul_f32_e32 v160, 0xbfb8aa3b, v160
	v_exp_f32_e32 v150, v150
	v_exp_f32_e32 v152, v152
	v_mul_f32_e32 v159, 0xbfb8aa3b, v159
	v_mul_f32_e32 v161, 0xbfb8aa3b, v161
	v_exp_f32_e32 v151, v151
	v_exp_f32_e32 v153, v153
	v_exp_f32_e32 v158, v158
	v_exp_f32_e32 v160, v160
	v_exp_f32_e32 v159, v159
	v_exp_f32_e32 v161, v161
	v_add_f32_e32 v150, 1.0, v150
	v_add_f32_e32 v152, 1.0, v152
	v_add_f32_e32 v151, 1.0, v151
	v_add_f32_e32 v153, 1.0, v153
	v_add_f32_e32 v158, 1.0, v158
	v_add_f32_e32 v160, 1.0, v160
	v_rcp_f32_e32 v150, v150
	v_rcp_f32_e32 v152, v152
	v_add_f32_e32 v159, 1.0, v159
	v_add_f32_e32 v161, 1.0, v161
	v_rcp_f32_e32 v151, v151
	v_rcp_f32_e32 v153, v153
	v_rcp_f32_e32 v158, v158
	v_rcp_f32_e32 v160, v160
	v_rcp_f32_e32 v159, v159
	v_rcp_f32_e32 v161, v161
	v_mul_f32_e32 v150, v67, v150
	v_mul_f32_e32 v152, v63, v152
	v_mul_f32_e32 v151, v69, v151
	v_mul_f32_e32 v153, v65, v153
	v_mul_f32_e32 v158, v66, v158
	v_mul_f32_e32 v160, v62, v160
	v_mul_f32_e32 v159, v68, v159
	v_mul_f32_e32 v161, v64, v161
	v_cvt_pk_bf16_f32 v150, v158, v150
	v_cvt_pk_bf16_f32 v151, v159, v151
	v_cvt_pk_bf16_f32 v152, v160, v152
	v_cvt_pk_bf16_f32 v153, v161, v153
	global_store_dwordx4 v[144:145], v[150:153], off offset:2048
	s_nop 1
	v_lshlrev_b32_e32 v150, 16, v154
	v_and_b32_e32 v151, 0xffff0000, v154
	v_lshlrev_b32_e32 v152, 16, v155
	v_and_b32_e32 v153, 0xffff0000, v155
	v_lshlrev_b32_e32 v154, 16, v156
	v_and_b32_e32 v155, 0xffff0000, v156
	v_lshlrev_b32_e32 v156, 16, v157
	v_and_b32_e32 v157, 0xffff0000, v157
	v_mul_f32_e32 v150, 0xbfb8aa3b, v150
	v_mul_f32_e32 v151, 0xbfb8aa3b, v151
	v_mul_f32_e32 v152, 0xbfb8aa3b, v152
	v_mul_f32_e32 v153, 0xbfb8aa3b, v153
	v_exp_f32_e32 v150, v150
	v_mul_f32_e32 v154, 0xbfb8aa3b, v154
	v_exp_f32_e32 v151, v151
	v_mul_f32_e32 v155, 0xbfb8aa3b, v155
	v_exp_f32_e32 v152, v152
	v_mul_f32_e32 v156, 0xbfb8aa3b, v156
	v_exp_f32_e32 v153, v153
	v_mul_f32_e32 v157, 0xbfb8aa3b, v157
	v_exp_f32_e32 v154, v154
	v_exp_f32_e32 v155, v155
	v_exp_f32_e32 v156, v156
	v_exp_f32_e32 v157, v157
	v_add_f32_e32 v150, 1.0, v150
	v_add_f32_e32 v151, 1.0, v151
	v_add_f32_e32 v152, 1.0, v152
	v_add_f32_e32 v153, 1.0, v153
	v_rcp_f32_e32 v150, v150
	v_add_f32_e32 v154, 1.0, v154
	v_rcp_f32_e32 v151, v151
	v_add_f32_e32 v155, 1.0, v155
	v_rcp_f32_e32 v152, v152
	v_add_f32_e32 v156, 1.0, v156
	v_rcp_f32_e32 v153, v153
	v_add_f32_e32 v157, 1.0, v157
	v_rcp_f32_e32 v154, v154
	v_rcp_f32_e32 v155, v155
	v_rcp_f32_e32 v156, v156
	v_rcp_f32_e32 v157, v157
	v_mul_f32_e32 v150, v58, v150
	v_mul_f32_e32 v151, v59, v151
	v_mul_f32_e32 v152, v60, v152
	v_mul_f32_e32 v153, v61, v153
	v_mul_f32_e32 v154, v54, v154
	v_mul_f32_e32 v155, v55, v155
	v_mul_f32_e32 v156, v56, v156
	v_mul_f32_e32 v157, v57, v157
	v_cvt_pk_bf16_f32 v150, v150, v151
	v_cvt_pk_bf16_f32 v151, v152, v153
	v_cvt_pk_bf16_f32 v152, v154, v155
	v_cvt_pk_bf16_f32 v153, v156, v157
	global_store_dwordx4 v[144:145], v[150:153], off offset:2304
	s_waitcnt vmcnt(2)
	v_lshlrev_b32_e32 v144, 16, v138
	v_and_b32_e32 v138, 0xffff0000, v138
	v_lshlrev_b32_e32 v145, 16, v139
	v_and_b32_e32 v139, 0xffff0000, v139
	v_lshlrev_b32_e32 v150, 16, v140
	v_and_b32_e32 v140, 0xffff0000, v140
	v_lshlrev_b32_e32 v151, 16, v141
	v_and_b32_e32 v141, 0xffff0000, v141
	v_mul_f32_e32 v138, 0xbfb8aa3b, v138
	v_mul_f32_e32 v144, 0xbfb8aa3b, v144
	v_exp_f32_e32 v138, v138
	v_mul_f32_e32 v140, 0xbfb8aa3b, v140
	v_mul_f32_e32 v139, 0xbfb8aa3b, v139
	v_mul_f32_e32 v141, 0xbfb8aa3b, v141
	v_exp_f32_e32 v144, v144
	v_mul_f32_e32 v150, 0xbfb8aa3b, v150
	v_exp_f32_e32 v140, v140
	v_mul_f32_e32 v145, 0xbfb8aa3b, v145
	v_mul_f32_e32 v151, 0xbfb8aa3b, v151
	v_exp_f32_e32 v139, v139
	v_exp_f32_e32 v141, v141
	v_exp_f32_e32 v150, v150
	v_exp_f32_e32 v145, v145
	v_exp_f32_e32 v151, v151
	v_add_f32_e32 v138, 1.0, v138
	v_add_f32_e32 v144, 1.0, v144
	v_rcp_f32_e32 v138, v138
	v_add_f32_e32 v140, 1.0, v140
	v_add_f32_e32 v139, 1.0, v139
	v_add_f32_e32 v141, 1.0, v141
	v_rcp_f32_e32 v144, v144
	v_add_f32_e32 v150, 1.0, v150
	v_rcp_f32_e32 v140, v140
	v_add_f32_e32 v145, 1.0, v145
	v_add_f32_e32 v151, 1.0, v151
	v_rcp_f32_e32 v139, v139
	v_rcp_f32_e32 v141, v141
	v_rcp_f32_e32 v150, v150
	v_rcp_f32_e32 v145, v145
	v_rcp_f32_e32 v151, v151
	v_mul_f32_e32 v138, v51, v138
	v_mul_f32_e32 v144, v50, v144
	v_mul_f32_e32 v140, v47, v140
	v_mul_f32_e32 v139, v53, v139
	v_mul_f32_e32 v141, v49, v141
	v_cvt_pk_bf16_f32 v138, v144, v138
	v_mul_f32_e32 v150, v46, v150
	v_mul_f32_e32 v145, v52, v145
	v_mul_f32_e32 v151, v48, v151
	v_cvt_pk_bf16_f32 v139, v145, v139
	v_cvt_pk_bf16_f32 v140, v150, v140
	v_cvt_pk_bf16_f32 v141, v151, v141
	global_store_dwordx4 v[142:143], v[138:141], off offset:2048
	s_nop 1
	v_lshlrev_b32_e32 v138, 16, v134
	v_and_b32_e32 v134, 0xffff0000, v134
	v_lshlrev_b32_e32 v139, 16, v135
	v_and_b32_e32 v135, 0xffff0000, v135
	v_lshlrev_b32_e32 v140, 16, v136
	v_and_b32_e32 v136, 0xffff0000, v136
	v_lshlrev_b32_e32 v141, 16, v137
	v_and_b32_e32 v137, 0xffff0000, v137
; __device__ __forceinline__ float sigmoidf_(float g) { return __builtin_amdgcn_rcpf(1.f + __expf(-g)); }
; __device__ __forceinline__ u32x4 pack8(const f32x4& a, const f32x4& b) { u32x4 w; w.x = cvt_pk_bf16(a[0], a[1]); w.y = cvt_pk_bf16(a[2], a[3]); w.z = cvt_pk_bf16(b[0], b[1]); w.w = cvt_pk_bf16(b[2], b[3]); return w; }
; __device__ __forceinline__ void unpack8(const u32x4& w, float (&v)[8]) { v[0] = bf_lo(w.x); v[1] = bf_hi(w.x); v[2] = bf_lo(w.y); v[3] = bf_hi(w.y); v[4] = bf_lo(w.z); v[5] = bf_hi(w.z); v[6] = bf_lo(w.w); v[7] = bf_hi(w.w); }
;     __device__ __forceinline__ void apply(const Ld& d, int row, int c0, int, int, int, const f32x4& a0, const f32x4& b0, const f32x4& a1, const f32x4& b1) const { half(d.g0, d.p0, row, c0, a0, b0); half(d.g1, d.p1, row, c0 + 128, a1, b1); }
;     __device__ __forceinline__ void operator()(const f32x4 (&acc)[2][2][4][2], const Unit& u, int wr, int wc, int fr, int fq) const {
;         const int c0 = u.pn * BM + wc * 32 + 8 * fq;
; #pragma unroll
;         for (int ai = 0; ai < 2; ++ai)
; #pragma unroll
;             for (int mp = 0; mp < 4; mp += 2) {
;                 typename F::Ld ld[2];
; #pragma unroll
;                 for (int m = 0; m < 2; ++m) f.load(ld[m], u.pm * BM + ai * HALF + wr * 64 + (mp + m) * 16 + fr, c0, u.pn, fq);
; #pragma unroll
;                 for (int m = 0; m < 2; ++m) f.apply(ld[m], u.pm * BM + ai * HALF + wr * 64 + (mp + m) * 16 + fr, c0, u.pn, wc, fq, acc[ai][0][mp + m][0], acc[ai][0][mp + m][1], acc[ai][1][mp + m][0], acc[ai][1][mp + m][1]);
;             }
;     }
;     __device__ __forceinline__ void half(const u32x4& gw, int row, int col, const f32x4& a, const f32x4& b) const {
;         float g[8]; unpack8(gw, g);
;         f32x4 r0, r1;
; #pragma unroll
;         for (int i = 0; i < 4; ++i) { r0[i] = a[i] * sigmoidf_(g[i]); r1[i] = b[i] * sigmoidf_(g[4 + i]); }
;         *(u32x4*)(proj + (size_t)row * PW + C_MPOOL + col) = pack8(r0, r1);
;     }
;     __device__ __forceinline__ void apply(const Ld& d, int row, int c0, int, int, int, const f32x4& a0, const f32x4& b0, const f32x4& a1, const f32x4& b1) const { half(d.g0, row, c0, a0, b0); half(d.g1, row, c0 + 128, a1, b1); }
	v_mul_f32_e32 v134, 0xbfb8aa3b, v134
	v_mul_f32_e32 v138, 0xbfb8aa3b, v138
	v_exp_f32_e32 v134, v134
	v_mul_f32_e32 v136, 0xbfb8aa3b, v136
	v_mul_f32_e32 v135, 0xbfb8aa3b, v135
	v_mul_f32_e32 v137, 0xbfb8aa3b, v137
	v_exp_f32_e32 v138, v138
	v_mul_f32_e32 v140, 0xbfb8aa3b, v140
	v_exp_f32_e32 v136, v136
	v_mul_f32_e32 v139, 0xbfb8aa3b, v139
	v_mul_f32_e32 v141, 0xbfb8aa3b, v141
	v_exp_f32_e32 v135, v135
	v_exp_f32_e32 v137, v137
	v_exp_f32_e32 v140, v140
	v_exp_f32_e32 v139, v139
	v_exp_f32_e32 v141, v141
	v_add_f32_e32 v134, 1.0, v134
	v_add_f32_e32 v138, 1.0, v138
	v_rcp_f32_e32 v134, v134
	v_add_f32_e32 v136, 1.0, v136
	v_add_f32_e32 v135, 1.0, v135
	v_add_f32_e32 v137, 1.0, v137
	v_rcp_f32_e32 v138, v138
	v_add_f32_e32 v140, 1.0, v140
	v_rcp_f32_e32 v136, v136
	v_add_f32_e32 v139, 1.0, v139
	v_add_f32_e32 v141, 1.0, v141
	v_rcp_f32_e32 v135, v135
	v_rcp_f32_e32 v137, v137
	v_rcp_f32_e32 v140, v140
	v_rcp_f32_e32 v139, v139
	v_rcp_f32_e32 v141, v141
	v_mul_f32_e32 v134, v43, v134
	v_mul_f32_e32 v138, v42, v138
	v_mul_f32_e32 v136, v39, v136
	v_mul_f32_e32 v135, v45, v135
	v_mul_f32_e32 v137, v41, v137
	v_cvt_pk_bf16_f32 v134, v138, v134
	v_mul_f32_e32 v140, v38, v140
	v_mul_f32_e32 v139, v44, v139
	v_mul_f32_e32 v141, v40, v141
	v_cvt_pk_bf16_f32 v135, v139, v135
	v_cvt_pk_bf16_f32 v136, v140, v136
	v_cvt_pk_bf16_f32 v137, v141, v137
	global_store_dwordx4 v[142:143], v[134:137], off offset:2304
	s_nop 1
	v_add_u32_e32 v134, 0xa0, v0
	v_mad_i64_i32 v[134:135], s[0:1], v134, s29, v[146:147]
	v_lshl_add_u64 v[144:145], v[134:135], 0, v[148:149]
	v_add_co_u32_e32 v134, vcc, s98, v144
	v_add_u32_e32 v0, 0xb0, v0
	s_nop 0
	v_addc_co_u32_e32 v135, vcc, 0, v145, vcc
	global_load_dwordx4 v[150:153], v[134:135], off offset:1024
	global_load_dwordx4 v[154:157], v[134:135], off offset:1280
	v_mad_i64_i32 v[134:135], s[0:1], v0, s29, v[146:147]
	v_lshl_add_u64 v[142:143], v[134:135], 0, v[148:149]
	v_add_co_u32_e32 v134, vcc, s98, v142
	s_waitcnt vmcnt(0)
	v_and_b32_e32 v146, 0xffff0000, v150
	v_addc_co_u32_e32 v135, vcc, 0, v143, vcc
	global_load_dwordx4 v[138:141], v[134:135], off offset:1024
	s_nop 0
	global_load_dwordx4 v[134:137], v[134:135], off offset:1280
	v_lshlrev_b32_e32 v147, 16, v151
	v_and_b32_e32 v148, 0xffff0000, v151
	v_lshlrev_b32_e32 v149, 16, v152
	v_lshlrev_b32_e32 v0, 16, v150
	v_and_b32_e32 v150, 0xffff0000, v152
	v_lshlrev_b32_e32 v151, 16, v153
	v_and_b32_e32 v152, 0xffff0000, v153
	v_mul_f32_e32 v149, 0xbfb8aa3b, v149
	v_mul_f32_e32 v146, 0xbfb8aa3b, v146
	v_mul_f32_e32 v147, 0xbfb8aa3b, v147
	v_mul_f32_e32 v148, 0xbfb8aa3b, v148
	v_mul_f32_e32 v0, 0xbfb8aa3b, v0
	v_exp_f32_e32 v149, v149
	v_exp_f32_e32 v146, v146
	v_mul_f32_e32 v150, 0xbfb8aa3b, v150
	v_exp_f32_e32 v147, v147
	v_mul_f32_e32 v151, 0xbfb8aa3b, v151
	v_exp_f32_e32 v148, v148
	v_mul_f32_e32 v152, 0xbfb8aa3b, v152
	v_exp_f32_e32 v0, v0
	v_exp_f32_e32 v150, v150
	v_exp_f32_e32 v151, v151
	v_exp_f32_e32 v152, v152
	v_add_f32_e32 v149, 1.0, v149
	v_add_f32_e32 v146, 1.0, v146
	v_add_f32_e32 v147, 1.0, v147
	v_add_f32_e32 v148, 1.0, v148
	v_add_f32_e32 v0, 1.0, v0
	v_rcp_f32_e32 v149, v149
	v_rcp_f32_e32 v146, v146
	v_add_f32_e32 v150, 1.0, v150
	v_rcp_f32_e32 v147, v147
	v_add_f32_e32 v151, 1.0, v151
	v_rcp_f32_e32 v148, v148
	v_add_f32_e32 v152, 1.0, v152
	v_rcp_f32_e32 v0, v0
	v_rcp_f32_e32 v150, v150
	v_rcp_f32_e32 v151, v151
	v_rcp_f32_e32 v152, v152
	v_mul_f32_e32 v149, v30, v149
	v_mul_f32_e32 v146, v35, v146
	v_mul_f32_e32 v147, v36, v147
	v_mul_f32_e32 v148, v37, v148
	v_mul_f32_e32 v0, v34, v0
	v_mul_f32_e32 v150, v31, v150
	v_mul_f32_e32 v151, v32, v151
	v_mul_f32_e32 v152, v33, v152
	v_cvt_pk_bf16_f32 v146, v0, v146
	v_cvt_pk_bf16_f32 v147, v147, v148
	v_cvt_pk_bf16_f32 v148, v149, v150
	v_cvt_pk_bf16_f32 v149, v151, v152
	global_store_dwordx4 v[144:145], v[146:149], off offset:2048
	v_lshlrev_b32_e32 v0, 16, v154
	v_and_b32_e32 v150, 0xffff0000, v156
	v_and_b32_e32 v146, 0xffff0000, v154
	v_lshlrev_b32_e32 v147, 16, v155
	v_and_b32_e32 v148, 0xffff0000, v155
	v_lshlrev_b32_e32 v149, 16, v156
	v_lshlrev_b32_e32 v151, 16, v157
	v_and_b32_e32 v152, 0xffff0000, v157
	v_mul_f32_e32 v0, 0xbfb8aa3b, v0
	v_mul_f32_e32 v149, 0xbfb8aa3b, v149
	v_mul_f32_e32 v146, 0xbfb8aa3b, v146
	v_mul_f32_e32 v147, 0xbfb8aa3b, v147
	v_mul_f32_e32 v148, 0xbfb8aa3b, v148
	v_exp_f32_e32 v0, v0
	v_exp_f32_e32 v149, v149
	v_exp_f32_e32 v146, v146
	v_mul_f32_e32 v150, 0xbfb8aa3b, v150
	v_exp_f32_e32 v147, v147
	v_mul_f32_e32 v151, 0xbfb8aa3b, v151
	v_exp_f32_e32 v148, v148
	v_mul_f32_e32 v152, 0xbfb8aa3b, v152
	v_exp_f32_e32 v150, v150
	v_exp_f32_e32 v151, v151
	v_exp_f32_e32 v152, v152
	v_add_f32_e32 v0, 1.0, v0
	v_add_f32_e32 v149, 1.0, v149
	v_add_f32_e32 v146, 1.0, v146
	v_add_f32_e32 v147, 1.0, v147
	v_add_f32_e32 v148, 1.0, v148
	v_rcp_f32_e32 v0, v0
	v_rcp_f32_e32 v149, v149
	v_rcp_f32_e32 v146, v146
	v_add_f32_e32 v150, 1.0, v150
	v_rcp_f32_e32 v147, v147
	v_add_f32_e32 v151, 1.0, v151
	v_rcp_f32_e32 v148, v148
	v_add_f32_e32 v152, 1.0, v152
	v_rcp_f32_e32 v150, v150
	v_rcp_f32_e32 v151, v151
	v_rcp_f32_e32 v152, v152
	v_mul_f32_e32 v0, v26, v0
	v_mul_f32_e32 v149, v22, v149
	v_mul_f32_e32 v146, v27, v146
	v_mul_f32_e32 v147, v28, v147
	v_mul_f32_e32 v148, v29, v148
	v_mul_f32_e32 v150, v23, v150
	v_mul_f32_e32 v151, v24, v151
	v_mul_f32_e32 v152, v25, v152
	v_cvt_pk_bf16_f32 v146, v0, v146
	v_cvt_pk_bf16_f32 v147, v147, v148
	v_cvt_pk_bf16_f32 v148, v149, v150
	v_cvt_pk_bf16_f32 v149, v151, v152
	global_store_dwordx4 v[144:145], v[146:149], off offset:2304
	s_waitcnt vmcnt(2)
; __device__ __forceinline__ u32x4 pack8(const f32x4& a, const f32x4& b) { u32x4 w; w.x = cvt_pk_bf16(a[0], a[1]); w.y = cvt_pk_bf16(a[2], a[3]); w.z = cvt_pk_bf16(b[0], b[1]); w.w = cvt_pk_bf16(b[2], b[3]); return w; }
; __device__ __forceinline__ void unpack8(const u32x4& w, float (&v)[8]) { v[0] = bf_lo(w.x); v[1] = bf_hi(w.x); v[2] = bf_lo(w.y); v[3] = bf_hi(w.y); v[4] = bf_lo(w.z); v[5] = bf_hi(w.z); v[6] = bf_lo(w.w); v[7] = bf_hi(w.w); }
;     __device__ __forceinline__ void apply(const Ld& d, int row, int c0, int, int, int, const f32x4& a0, const f32x4& b0, const f32x4& a1, const f32x4& b1) const { half(d.g0, d.p0, row, c0, a0, b0); half(d.g1, d.p1, row, c0 + 128, a1, b1); }
; __device__ __forceinline__ float sigmoidf_(float g) { return __builtin_amdgcn_rcpf(1.f + __expf(-g)); }
; __device__ __forceinline__ float siluf_(float z) { return z * sigmoidf_(z); }
;     __device__ __forceinline__ void half(const u32x4& gw, int row, int col, const f32x4& a, const f32x4& b) const {
;         float g[8]; unpack8(gw, g);
;         f32x4 r0, r1;
; #pragma unroll
;         for (int i = 0; i < 4; ++i) { r0[i] = a[i] * sigmoidf_(g[i]); r1[i] = b[i] * sigmoidf_(g[4 + i]); }
;         *(u32x4*)(proj + (size_t)row * PW + C_MPOOL + col) = pack8(r0, r1);
;     }
;     __device__ __forceinline__ void apply(const Ld& d, int row, int c0, int, int, int, const f32x4& a0, const f32x4& b0, const f32x4& a1, const f32x4& b1) const { half(d.g0, row, c0, a0, b0); half(d.g1, row, c0 + 128, a1, b1); }
	v_lshlrev_b32_e32 v0, 16, v138
	v_and_b32_e32 v138, 0xffff0000, v138
	v_lshlrev_b32_e32 v144, 16, v139
	v_and_b32_e32 v139, 0xffff0000, v139
	v_lshlrev_b32_e32 v145, 16, v140
	v_and_b32_e32 v140, 0xffff0000, v140
	v_lshlrev_b32_e32 v146, 16, v141
	v_and_b32_e32 v141, 0xffff0000, v141
	v_mul_f32_e32 v138, 0xbfb8aa3b, v138
	v_mul_f32_e32 v140, 0xbfb8aa3b, v140
	v_mul_f32_e32 v139, 0xbfb8aa3b, v139
	v_mul_f32_e32 v0, 0xbfb8aa3b, v0
	v_mul_f32_e32 v145, 0xbfb8aa3b, v145
	v_exp_f32_e32 v138, v138
	v_exp_f32_e32 v140, v140
	v_mul_f32_e32 v144, 0xbfb8aa3b, v144
	v_exp_f32_e32 v139, v139
	v_mul_f32_e32 v141, 0xbfb8aa3b, v141
	v_exp_f32_e32 v0, v0
	v_exp_f32_e32 v145, v145
	v_exp_f32_e32 v144, v144
	v_mul_f32_e32 v146, 0xbfb8aa3b, v146
	v_exp_f32_e32 v141, v141
	v_exp_f32_e32 v146, v146
	v_add_f32_e32 v138, 1.0, v138
	v_add_f32_e32 v140, 1.0, v140
	v_add_f32_e32 v139, 1.0, v139
	v_add_f32_e32 v0, 1.0, v0
	v_add_f32_e32 v145, 1.0, v145
	v_rcp_f32_e32 v138, v138
	v_rcp_f32_e32 v140, v140
	v_add_f32_e32 v144, 1.0, v144
	v_rcp_f32_e32 v139, v139
	v_add_f32_e32 v141, 1.0, v141
	v_rcp_f32_e32 v0, v0
	v_rcp_f32_e32 v145, v145
	v_rcp_f32_e32 v144, v144
	v_add_f32_e32 v146, 1.0, v146
	v_rcp_f32_e32 v141, v141
	v_rcp_f32_e32 v146, v146
	v_mul_f32_e32 v138, v19, v138
	v_mul_f32_e32 v140, v11, v140
	v_mul_f32_e32 v139, v21, v139
	v_mul_f32_e32 v0, v18, v0
	v_mul_f32_e32 v145, v10, v145
	v_mul_f32_e32 v144, v20, v144
	v_mul_f32_e32 v141, v13, v141
	v_cvt_pk_bf16_f32 v138, v0, v138
	v_cvt_pk_bf16_f32 v139, v144, v139
	v_cvt_pk_bf16_f32 v140, v145, v140
	v_mul_f32_e32 v146, v12, v146
	v_cvt_pk_bf16_f32 v141, v146, v141
	global_store_dwordx4 v[142:143], v[138:141], off offset:2048
	v_lshlrev_b32_e32 v0, 16, v134
	v_and_b32_e32 v134, 0xffff0000, v134
	v_lshlrev_b32_e32 v138, 16, v135
	v_and_b32_e32 v135, 0xffff0000, v135
	v_lshlrev_b32_e32 v139, 16, v136
	v_and_b32_e32 v136, 0xffff0000, v136
	v_lshlrev_b32_e32 v140, 16, v137
	v_and_b32_e32 v137, 0xffff0000, v137
	v_mul_f32_e32 v134, 0xbfb8aa3b, v134
	v_mul_f32_e32 v136, 0xbfb8aa3b, v136
	v_mul_f32_e32 v135, 0xbfb8aa3b, v135
	v_mul_f32_e32 v137, 0xbfb8aa3b, v137
	v_mul_f32_e32 v0, 0xbfb8aa3b, v0
	v_mul_f32_e32 v139, 0xbfb8aa3b, v139
	v_exp_f32_e32 v134, v134
	v_exp_f32_e32 v136, v136
	v_mul_f32_e32 v138, 0xbfb8aa3b, v138
	v_mul_f32_e32 v140, 0xbfb8aa3b, v140
	v_exp_f32_e32 v135, v135
	v_exp_f32_e32 v137, v137
	v_exp_f32_e32 v0, v0
	v_exp_f32_e32 v139, v139
	v_exp_f32_e32 v138, v138
	v_exp_f32_e32 v140, v140
	v_add_f32_e32 v134, 1.0, v134
	v_add_f32_e32 v136, 1.0, v136
	v_add_f32_e32 v135, 1.0, v135
	v_add_f32_e32 v137, 1.0, v137
	v_add_f32_e32 v0, 1.0, v0
	v_add_f32_e32 v139, 1.0, v139
	v_rcp_f32_e32 v134, v134
	v_rcp_f32_e32 v136, v136
	v_add_f32_e32 v138, 1.0, v138
	v_add_f32_e32 v140, 1.0, v140
	v_rcp_f32_e32 v135, v135
	v_rcp_f32_e32 v137, v137
	v_rcp_f32_e32 v0, v0
	v_rcp_f32_e32 v139, v139
	v_rcp_f32_e32 v138, v138
	v_rcp_f32_e32 v140, v140
	v_mul_f32_e32 v134, v7, v134
	v_mul_f32_e32 v136, v3, v136
	v_mul_f32_e32 v135, v9, v135
	v_mul_f32_e32 v137, v5, v137
	v_mul_f32_e32 v0, v6, v0
	v_mul_f32_e32 v139, v2, v139
	v_mul_f32_e32 v138, v8, v138
	v_mul_f32_e32 v140, v4, v140
	v_cvt_pk_bf16_f32 v134, v0, v134
	v_cvt_pk_bf16_f32 v135, v138, v135
	v_cvt_pk_bf16_f32 v136, v139, v136
	v_cvt_pk_bf16_f32 v137, v140, v137
	global_store_dwordx4 v[142:143], v[134:137], off offset:2304
